# GEMM K-loops: removed the 24 redundant back-to-back s_setprio 0 / s_setprio 1 pairs between the two 16-MFMA clusters of a super-phase (priority stays raised across both)
# baseline (speedup 1.0000x reference)
; #define PG8_STAGE(bufoff, gbase, voff) do { _Pragma("unroll") for (int _i = 0; _i < 2; ++_i) \
;         __builtin_amdgcn_global_load_lds((const unsigned*)((const char*)(gbase) + (voff)[_i]), (PG8_LAS unsigned*)(lds + (bufoff) + ldsw + _i * 8192), 16, 0, 0); } while (0)
; #define PG8_LDA(dst, b, h) do { _Pragma("unroll") for (int m = 0; m < 4; ++m) _Pragma("unroll") for (int k = 0; k < 2; ++k) dst[m][k] = *(const PG8_LAS bf16x8*)(lds + PG8_SA(b, h) + aoff + m * 2048 + k * 1024); } while (0)
; #define PG8_LDB(dst, b, h) do { _Pragma("unroll") for (int n = 0; n < 2; ++n) _Pragma("unroll") for (int k = 0; k < 2; ++k) dst[n][k] = *(const PG8_LAS bf16x8*)(lds + PG8_SB(b, h) + boff + n * 2048 + k * 1024); } while (0)
; #define PG8_WAIT_V(n) asm volatile("s_waitcnt vmcnt(" #n ")" ::: "memory")
; #define PG8_WAIT_L(n) asm volatile("s_waitcnt lgkmcnt(" #n ")" ::: "memory")
; #define PG8_BAR __builtin_amdgcn_s_barrier()
; #define PG8_SCHED __builtin_amdgcn_sched_barrier(0)
;     ...
;             if constexpr (SP2) {
;             PG8_LDB(B0, 0, 0); PG8_LDB(B1, 0, 1); PG8_SCHED; PG8_LDA(At, 0, 0); PG8_STAGE(PG8_SA(1, 1), a1 + hstepA, voffA);
;             PG8_WAIT_V(8); PG8_WAIT_L(0); PG8_BAR; PG8_MMA(0, 0, At, B0); PG8_MMA(0, 1, At, B1); PG8_BAR; PG8_SCHED;
;             PG8_LDA(At, 0, 1); PG8_STAGE(PG8_SB(0, 0), b2, voffB); PG8_STAGE(PG8_SB(0, 1), b2 + hstepB, voffB); PG8_STAGE(PG8_SA(0, 0), a2, voffA);
;             PG8_WAIT_V(8); PG8_WAIT_L(0); PG8_BAR; PG8_MMA(1, 0, At, B0); PG8_MMA(1, 1, At, B1); PG8_BAR; PG8_SCHED;
.LBB0_328:
	s_add_u32 s22, s18, 0xfffe0080
	s_addc_u32 s23, s19, -1
	s_add_i32 s40, 0, 0x10000
	s_cmp_eq_u32 s33, 4
	s_cselect_b32 s39, s11, s23
	s_cselect_b32 s38, s21, s22
	s_cselect_b32 s23, s25, s29
	s_cselect_b32 s22, s26, s27
	s_add_i32 s42, 0, 0x14000
	v_add_u32_e32 v70, s40, v215
	v_add_u32_e32 v168, s42, v215
	ds_read_b128 v[44:47], v70
	ds_read_b128 v[56:59], v70 offset:1024
	ds_read_b128 v[66:69], v70 offset:2048
	ds_read_b128 v[70:73], v70 offset:3072
	s_waitcnt lgkmcnt(0)
	ds_read_b128 v[146:149], v168
	ds_read_b128 v[160:163], v168 offset:1024
	ds_read_b128 v[164:167], v168 offset:2048
	ds_read_b128 v[168:171], v168 offset:3072
	v_lshl_add_u64 v[222:223], s[18:19], 0, v[156:157]
	s_add_i32 m0, s49, 0xc000
	ds_read_b128 v[172:175], v216
	ds_read_b128 v[176:179], v216 offset:1024
	ds_read_b128 v[180:183], v216 offset:2048
	ds_read_b128 v[184:187], v216 offset:3072
	ds_read_b128 v[188:191], v216 offset:4096
	ds_read_b128 v[206:209], v216 offset:5120
	ds_read_b128 v[210:213], v216 offset:6144
	ds_read_b128 v[218:221], v216 offset:7168
	global_load_lds_dwordx4 v[222:223], off
	v_lshl_add_u64 v[222:223], s[18:19], 0, v[158:159]
	s_add_i32 m0, s49, 0xe000
	s_nop 0
	global_load_lds_dwordx4 v[222:223], off
	s_waitcnt vmcnt(8)
	s_waitcnt lgkmcnt(0)
	s_barrier
	s_setprio 1
	s_waitcnt lgkmcnt(0)
	v_mfma_i32_16x16x64_i8 v[142:145], v[44:47], v[172:175], v[142:145]
	v_mfma_i32_16x16x64_i8 v[138:141], v[66:69], v[172:175], v[138:141]
	v_mfma_i32_16x16x64_i8 v[126:129], v[44:47], v[180:183], v[126:129]
	v_mfma_i32_16x16x64_i8 v[122:125], v[66:69], v[180:183], v[122:125]
	v_mfma_i32_16x16x64_i8 v[110:113], v[44:47], v[188:191], v[110:113]
	v_mfma_i32_16x16x64_i8 v[106:109], v[66:69], v[188:191], v[106:109]
	v_mfma_i32_16x16x64_i8 v[94:97], v[44:47], v[210:213], v[94:97]
	v_mfma_i32_16x16x64_i8 v[90:93], v[66:69], v[210:213], v[90:93]
	v_mfma_i32_16x16x64_i8 v[142:145], v[56:59], v[176:179], v[142:145]
	v_mfma_i32_16x16x64_i8 v[138:141], v[70:73], v[176:179], v[138:141]
	v_mfma_i32_16x16x64_i8 v[126:129], v[56:59], v[184:187], v[126:129]
	v_mfma_i32_16x16x64_i8 v[122:125], v[70:73], v[184:187], v[122:125]
	v_mfma_i32_16x16x64_i8 v[110:113], v[56:59], v[206:209], v[110:113]
	v_mfma_i32_16x16x64_i8 v[106:109], v[70:73], v[206:209], v[106:109]
	v_mfma_i32_16x16x64_i8 v[94:97], v[56:59], v[218:221], v[94:97]
	v_mfma_i32_16x16x64_i8 v[90:93], v[70:73], v[218:221], v[90:93]
	v_mfma_i32_16x16x64_i8 v[134:137], v[146:149], v[172:175], v[134:137]
	v_mfma_i32_16x16x64_i8 v[130:133], v[164:167], v[172:175], v[130:133]
	v_mfma_i32_16x16x64_i8 v[118:121], v[146:149], v[180:183], v[118:121]
	v_mfma_i32_16x16x64_i8 v[114:117], v[164:167], v[180:183], v[114:117]
	v_mfma_i32_16x16x64_i8 v[102:105], v[146:149], v[188:191], v[102:105]
	v_mfma_i32_16x16x64_i8 v[98:101], v[164:167], v[188:191], v[98:101]
	v_mfma_i32_16x16x64_i8 v[86:89], v[146:149], v[210:213], v[86:89]
	v_mfma_i32_16x16x64_i8 v[82:85], v[164:167], v[210:213], v[82:85]
	v_mfma_i32_16x16x64_i8 v[134:137], v[160:163], v[176:179], v[134:137]
	v_mfma_i32_16x16x64_i8 v[130:133], v[168:171], v[176:179], v[130:133]
	v_mfma_i32_16x16x64_i8 v[118:121], v[160:163], v[184:187], v[118:121]
	v_mfma_i32_16x16x64_i8 v[114:117], v[168:171], v[184:187], v[114:117]
	v_mfma_i32_16x16x64_i8 v[102:105], v[160:163], v[206:209], v[102:105]
	v_mfma_i32_16x16x64_i8 v[98:101], v[168:171], v[206:209], v[98:101]
	v_mfma_i32_16x16x64_i8 v[86:89], v[160:163], v[218:221], v[86:89]
	v_mfma_i32_16x16x64_i8 v[82:85], v[168:171], v[218:221], v[82:85]
	s_setprio 0
	s_barrier
	s_add_i32 s40, s40, s48
	v_lshl_add_u64 v[222:223], s[22:23], 0, v[64:65]
	s_mov_b32 m0, s40
	ds_read_b128 v[172:175], v216 offset:16384
	ds_read_b128 v[176:179], v216 offset:17408
	ds_read_b128 v[180:183], v216 offset:18432
	ds_read_b128 v[184:187], v216 offset:19456
	ds_read_b128 v[188:191], v216 offset:20480
	ds_read_b128 v[206:209], v216 offset:21504
	ds_read_b128 v[210:213], v216 offset:22528
	ds_read_b128 v[218:221], v216 offset:23552
	global_load_lds_dwordx4 v[222:223], off
	s_add_i32 m0, s40, 0x2000
	s_add_u32 s40, s22, 0x20000
	v_lshl_add_u64 v[224:225], s[22:23], 0, v[150:151]
	s_addc_u32 s41, s23, 0
	s_add_i32 s42, s42, s48
	global_load_lds_dwordx4 v[224:225], off
	v_lshl_add_u64 v[226:227], s[40:41], 0, v[64:65]
	s_mov_b32 m0, s42
	v_lshl_add_u64 v[228:229], s[38:39], 0, v[152:153]
	global_load_lds_dwordx4 v[226:227], off
	v_lshl_add_u64 v[226:227], s[40:41], 0, v[150:151]
	s_add_i32 m0, s42, 0x2000
	s_nop 0
	global_load_lds_dwordx4 v[226:227], off
	v_lshl_add_u64 v[226:227], s[38:39], 0, v[154:155]
	s_mov_b32 m0, s49
	s_nop 0
	global_load_lds_dwordx4 v[226:227], off
	s_mov_b32 m0, s50
	s_nop 0
	global_load_lds_dwordx4 v[228:229], off
	s_waitcnt vmcnt(8)
	s_waitcnt lgkmcnt(0)
	s_barrier
; #define PG8_STAGE(bufoff, gbase, voff) do { _Pragma("unroll") for (int _i = 0; _i < 2; ++_i) \
;         __builtin_amdgcn_global_load_lds((const unsigned*)((const char*)(gbase) + (voff)[_i]), (PG8_LAS unsigned*)(lds + (bufoff) + ldsw + _i * 8192), 16, 0, 0); } while (0)
; #define PG8_LDA(dst, b, h) do { _Pragma("unroll") for (int m = 0; m < 4; ++m) _Pragma("unroll") for (int k = 0; k < 2; ++k) dst[m][k] = *(const PG8_LAS bf16x8*)(lds + PG8_SA(b, h) + aoff + m * 2048 + k * 1024); } while (0)
; #define PG8_LDB(dst, b, h) do { _Pragma("unroll") for (int n = 0; n < 2; ++n) _Pragma("unroll") for (int k = 0; k < 2; ++k) dst[n][k] = *(const PG8_LAS bf16x8*)(lds + PG8_SB(b, h) + boff + n * 2048 + k * 1024); } while (0)
; #define PG8_WAIT_V(n) asm volatile("s_waitcnt vmcnt(" #n ")" ::: "memory")
; #define PG8_WAIT_L(n) asm volatile("s_waitcnt lgkmcnt(" #n ")" ::: "memory")
; #define PG8_BAR __builtin_amdgcn_s_barrier()
; #define PG8_SCHED __builtin_amdgcn_sched_barrier(0)
;     ...
;             PG8_WAIT_V(8); PG8_WAIT_L(0); PG8_BAR; PG8_MMA(0, 0, At, B0); PG8_MMA(0, 1, At, B1); PG8_BAR; PG8_SCHED;
;             PG8_LDA(At, 0, 1); PG8_STAGE(PG8_SB(0, 0), b2, voffB); PG8_STAGE(PG8_SB(0, 1), b2 + hstepB, voffB); PG8_STAGE(PG8_SA(0, 0), a2, voffA);
;             PG8_WAIT_V(8); PG8_WAIT_L(0); PG8_BAR; PG8_MMA(1, 0, At, B0); PG8_MMA(1, 1, At, B1); PG8_BAR; PG8_SCHED;
;             PG8_LDB(B0, 1, 0); PG8_LDB(B1, 1, 1); PG8_SCHED; PG8_LDA(At, 1, 0); PG8_STAGE(PG8_SA(0, 1), a2 + hstepA, voffA);
;             PG8_WAIT_V(8); PG8_WAIT_L(0); PG8_BAR; PG8_MMA(0, 0, At, B0); PG8_MMA(0, 1, At, B1); PG8_BAR; PG8_SCHED;
	s_setprio 1
	s_waitcnt lgkmcnt(0)
	v_mfma_i32_16x16x64_i8 v[78:81], v[44:47], v[172:175], v[78:81]
	v_mfma_i32_16x16x64_i8 v[74:77], v[66:69], v[172:175], v[74:77]
	v_mfma_i32_16x16x64_i8 v[48:51], v[44:47], v[180:183], v[48:51]
	v_mfma_i32_16x16x64_i8 v[40:43], v[66:69], v[180:183], v[40:43]
	v_mfma_i32_16x16x64_i8 v[28:31], v[44:47], v[188:191], v[28:31]
	v_mfma_i32_16x16x64_i8 v[24:27], v[66:69], v[188:191], v[24:27]
	v_mfma_i32_16x16x64_i8 v[12:15], v[44:47], v[210:213], v[12:15]
	v_mfma_i32_16x16x64_i8 v[8:11], v[66:69], v[210:213], v[8:11]
	v_mfma_i32_16x16x64_i8 v[78:81], v[56:59], v[176:179], v[78:81]
	v_mfma_i32_16x16x64_i8 v[74:77], v[70:73], v[176:179], v[74:77]
	v_mfma_i32_16x16x64_i8 v[48:51], v[56:59], v[184:187], v[48:51]
	v_mfma_i32_16x16x64_i8 v[40:43], v[70:73], v[184:187], v[40:43]
	v_mfma_i32_16x16x64_i8 v[28:31], v[56:59], v[206:209], v[28:31]
	v_mfma_i32_16x16x64_i8 v[24:27], v[70:73], v[206:209], v[24:27]
	v_mfma_i32_16x16x64_i8 v[12:15], v[56:59], v[218:221], v[12:15]
	v_mfma_i32_16x16x64_i8 v[8:11], v[70:73], v[218:221], v[8:11]
	v_mfma_i32_16x16x64_i8 v[52:55], v[164:167], v[172:175], v[52:55]
	v_mfma_i32_16x16x64_i8 v[36:39], v[146:149], v[180:183], v[36:39]
	v_mfma_i32_16x16x64_i8 v[32:35], v[164:167], v[180:183], v[32:35]
	v_mfma_i32_16x16x64_i8 v[20:23], v[146:149], v[188:191], v[20:23]
	v_mfma_i32_16x16x64_i8 v[16:19], v[164:167], v[188:191], v[16:19]
	v_mfma_i32_16x16x64_i8 v[4:7], v[146:149], v[210:213], v[4:7]
	v_mfma_i32_16x16x64_i8 v[0:3], v[164:167], v[210:213], v[0:3]
	v_mfma_i32_16x16x64_i8 v[44:47], v[146:149], v[172:175], v[60:63]
	v_mfma_i32_16x16x64_i8 v[52:55], v[168:171], v[176:179], v[52:55]
	v_mfma_i32_16x16x64_i8 v[36:39], v[160:163], v[184:187], v[36:39]
	v_mfma_i32_16x16x64_i8 v[32:35], v[168:171], v[184:187], v[32:35]
	v_mfma_i32_16x16x64_i8 v[20:23], v[160:163], v[206:209], v[20:23]
	v_mfma_i32_16x16x64_i8 v[16:19], v[168:171], v[206:209], v[16:19]
	v_mfma_i32_16x16x64_i8 v[4:7], v[160:163], v[218:221], v[4:7]
	v_mfma_i32_16x16x64_i8 v[0:3], v[168:171], v[218:221], v[0:3]
	v_mfma_i32_16x16x64_i8 v[44:47], v[160:163], v[176:179], v[44:47]
	s_setprio 0
	s_barrier
	s_add_i32 s40, 0, 0x18000
	s_add_i32 s41, 0, 0x1c000
	v_add_u32_e32 v70, s40, v215
	v_add_u32_e32 v168, s41, v215
	ds_read_b128 v[56:59], v70
	ds_read_b128 v[60:63], v70 offset:1024
	ds_read_b128 v[66:69], v70 offset:2048
	ds_read_b128 v[70:73], v70 offset:3072
	ds_read_b128 v[146:149], v168
	ds_read_b128 v[160:163], v168 offset:1024
	ds_read_b128 v[164:167], v168 offset:2048
	ds_read_b128 v[168:171], v168 offset:3072
	s_add_u32 s38, s38, 0x20000
	s_addc_u32 s39, s39, 0
	s_mov_b32 m0, s51
	v_lshl_add_u64 v[230:231], s[38:39], 0, v[154:155]
	ds_read_b128 v[172:175], v216 offset:32768
	ds_read_b128 v[176:179], v216 offset:33792
	ds_read_b128 v[180:183], v216 offset:34816
	ds_read_b128 v[184:187], v216 offset:35840
	ds_read_b128 v[188:191], v216 offset:36864
	ds_read_b128 v[206:209], v216 offset:37888
	ds_read_b128 v[210:213], v216 offset:38912
	ds_read_b128 v[218:221], v216 offset:39936
	global_load_lds_dwordx4 v[230:231], off
	v_lshl_add_u64 v[230:231], s[38:39], 0, v[152:153]
	s_mov_b32 m0, s52
	s_nop 0
	global_load_lds_dwordx4 v[230:231], off
	s_waitcnt vmcnt(8)
	s_waitcnt lgkmcnt(0)
	s_barrier
	s_setprio 1
	s_waitcnt lgkmcnt(0)
	v_mfma_i32_16x16x64_i8 v[142:145], v[56:59], v[172:175], v[142:145]
	v_mfma_i32_16x16x64_i8 v[138:141], v[66:69], v[172:175], v[138:141]
	v_mfma_i32_16x16x64_i8 v[126:129], v[56:59], v[180:183], v[126:129]
	v_mfma_i32_16x16x64_i8 v[122:125], v[66:69], v[180:183], v[122:125]
	v_mfma_i32_16x16x64_i8 v[110:113], v[56:59], v[188:191], v[110:113]
	v_mfma_i32_16x16x64_i8 v[106:109], v[66:69], v[188:191], v[106:109]
	v_mfma_i32_16x16x64_i8 v[94:97], v[56:59], v[210:213], v[94:97]
	v_mfma_i32_16x16x64_i8 v[90:93], v[66:69], v[210:213], v[90:93]
	v_mfma_i32_16x16x64_i8 v[142:145], v[60:63], v[176:179], v[142:145]
	v_mfma_i32_16x16x64_i8 v[138:141], v[70:73], v[176:179], v[138:141]
	v_mfma_i32_16x16x64_i8 v[126:129], v[60:63], v[184:187], v[126:129]
	v_mfma_i32_16x16x64_i8 v[122:125], v[70:73], v[184:187], v[122:125]
	v_mfma_i32_16x16x64_i8 v[110:113], v[60:63], v[206:209], v[110:113]
	v_mfma_i32_16x16x64_i8 v[106:109], v[70:73], v[206:209], v[106:109]
	v_mfma_i32_16x16x64_i8 v[94:97], v[60:63], v[218:221], v[94:97]
	v_mfma_i32_16x16x64_i8 v[90:93], v[70:73], v[218:221], v[90:93]
	v_mfma_i32_16x16x64_i8 v[134:137], v[146:149], v[172:175], v[134:137]
	v_mfma_i32_16x16x64_i8 v[130:133], v[164:167], v[172:175], v[130:133]
	v_mfma_i32_16x16x64_i8 v[118:121], v[146:149], v[180:183], v[118:121]
	v_mfma_i32_16x16x64_i8 v[114:117], v[164:167], v[180:183], v[114:117]
	v_mfma_i32_16x16x64_i8 v[102:105], v[146:149], v[188:191], v[102:105]
	v_mfma_i32_16x16x64_i8 v[98:101], v[164:167], v[188:191], v[98:101]
	v_mfma_i32_16x16x64_i8 v[86:89], v[146:149], v[210:213], v[86:89]
	v_mfma_i32_16x16x64_i8 v[82:85], v[164:167], v[210:213], v[82:85]
	v_mfma_i32_16x16x64_i8 v[134:137], v[160:163], v[176:179], v[134:137]
	v_mfma_i32_16x16x64_i8 v[130:133], v[168:171], v[176:179], v[130:133]
	v_mfma_i32_16x16x64_i8 v[118:121], v[160:163], v[184:187], v[118:121]
	v_mfma_i32_16x16x64_i8 v[114:117], v[168:171], v[184:187], v[114:117]
	v_mfma_i32_16x16x64_i8 v[102:105], v[160:163], v[206:209], v[102:105]
	v_mfma_i32_16x16x64_i8 v[98:101], v[168:171], v[206:209], v[98:101]
	v_mfma_i32_16x16x64_i8 v[86:89], v[160:163], v[218:221], v[86:89]
	v_mfma_i32_16x16x64_i8 v[82:85], v[168:171], v[218:221], v[82:85]
	s_setprio 0
	s_barrier
; #define PG8_STAGE(bufoff, gbase, voff) do { _Pragma("unroll") for (int _i = 0; _i < 2; ++_i) \
;         __builtin_amdgcn_global_load_lds((const unsigned*)((const char*)(gbase) + (voff)[_i]), (PG8_LAS unsigned*)(lds + (bufoff) + ldsw + _i * 8192), 16, 0, 0); } while (0)
; #define PG8_LDA(dst, b, h) do { _Pragma("unroll") for (int m = 0; m < 4; ++m) _Pragma("unroll") for (int k = 0; k < 2; ++k) dst[m][k] = *(const PG8_LAS bf16x8*)(lds + PG8_SA(b, h) + aoff + m * 2048 + k * 1024); } while (0)
; #define PG8_WAIT_V(n) asm volatile("s_waitcnt vmcnt(" #n ")" ::: "memory")
; #define PG8_WAIT_L(n) asm volatile("s_waitcnt lgkmcnt(" #n ")" ::: "memory")
; #define PG8_BAR __builtin_amdgcn_s_barrier()
; #define PG8_SCHED __builtin_amdgcn_sched_barrier(0)
;     ...
;             PG8_WAIT_V(8); PG8_WAIT_L(0); PG8_BAR; PG8_MMA(0, 0, At, B0); PG8_MMA(0, 1, At, B1); PG8_BAR; PG8_SCHED;
;             PG8_LDA(At, 1, 1); PG8_STAGE(PG8_SB(1, 0), b3, voffB); PG8_STAGE(PG8_SB(1, 1), b3 + hstepB, voffB); PG8_STAGE(PG8_SA(1, 0), a3, voffA);
;             PG8_WAIT_V(8); PG8_WAIT_L(0); PG8_BAR; PG8_MMA(1, 0, At, B0); PG8_MMA(1, 1, At, B1); PG8_BAR; PG8_SCHED;
	s_add_i32 s38, s40, s48
	v_lshl_add_u64 v[222:223], v[222:223], 0, s[44:45]
	s_mov_b32 m0, s38
	ds_read_b128 v[172:175], v216 offset:49152
	ds_read_b128 v[176:179], v216 offset:50176
	ds_read_b128 v[180:183], v216 offset:51200
	ds_read_b128 v[184:187], v216 offset:52224
	ds_read_b128 v[188:191], v216 offset:53248
	ds_read_b128 v[206:209], v216 offset:54272
	ds_read_b128 v[210:213], v216 offset:55296
	ds_read_b128 v[218:221], v216 offset:56320
	global_load_lds_dwordx4 v[222:223], off
	s_add_i32 m0, s38, 0x2000
	s_add_u32 s22, s22, 0x20080
	v_lshl_add_u64 v[222:223], v[224:225], 0, s[44:45]
	s_addc_u32 s23, s23, 0
	s_add_i32 s38, s41, s48
	global_load_lds_dwordx4 v[222:223], off
	v_lshl_add_u64 v[222:223], s[22:23], 0, v[64:65]
	s_mov_b32 m0, s38
	s_nop 0
	global_load_lds_dwordx4 v[222:223], off
	v_lshl_add_u64 v[222:223], s[22:23], 0, v[150:151]
	s_add_i32 m0, s38, 0x2000
	s_nop 0
	global_load_lds_dwordx4 v[222:223], off
	v_lshl_add_u64 v[222:223], v[226:227], 0, s[44:45]
	s_mov_b32 m0, s58
	s_nop 0
	global_load_lds_dwordx4 v[222:223], off
	v_lshl_add_u64 v[222:223], v[228:229], 0, s[44:45]
	s_mov_b32 m0, s59
	s_nop 0
	global_load_lds_dwordx4 v[222:223], off
	s_waitcnt vmcnt(8)
	s_waitcnt lgkmcnt(0)
	s_barrier
	s_setprio 1
	s_waitcnt lgkmcnt(0)
	v_mfma_i32_16x16x64_i8 v[78:81], v[56:59], v[172:175], v[78:81]
	v_mfma_i32_16x16x64_i8 v[74:77], v[66:69], v[172:175], v[74:77]
	v_mfma_i32_16x16x64_i8 v[48:51], v[56:59], v[180:183], v[48:51]
	v_mfma_i32_16x16x64_i8 v[40:43], v[66:69], v[180:183], v[40:43]
	v_mfma_i32_16x16x64_i8 v[28:31], v[56:59], v[188:191], v[28:31]
	v_mfma_i32_16x16x64_i8 v[24:27], v[66:69], v[188:191], v[24:27]
	v_mfma_i32_16x16x64_i8 v[12:15], v[56:59], v[210:213], v[12:15]
	v_mfma_i32_16x16x64_i8 v[8:11], v[66:69], v[210:213], v[8:11]
	v_mfma_i32_16x16x64_i8 v[78:81], v[60:63], v[176:179], v[78:81]
	v_mfma_i32_16x16x64_i8 v[74:77], v[70:73], v[176:179], v[74:77]
	v_mfma_i32_16x16x64_i8 v[48:51], v[60:63], v[184:187], v[48:51]
	v_mfma_i32_16x16x64_i8 v[40:43], v[70:73], v[184:187], v[40:43]
	v_mfma_i32_16x16x64_i8 v[28:31], v[60:63], v[206:209], v[28:31]
	v_mfma_i32_16x16x64_i8 v[24:27], v[70:73], v[206:209], v[24:27]
	v_mfma_i32_16x16x64_i8 v[12:15], v[60:63], v[218:221], v[12:15]
	v_mfma_i32_16x16x64_i8 v[8:11], v[70:73], v[218:221], v[8:11]
	v_mfma_i32_16x16x64_i8 v[44:47], v[146:149], v[172:175], v[44:47]
	v_mfma_i32_16x16x64_i8 v[60:63], v[160:163], v[176:179], v[44:47]
	v_mfma_i32_16x16x64_i8 v[44:47], v[164:167], v[172:175], v[52:55]
	v_mfma_i32_16x16x64_i8 v[36:39], v[146:149], v[180:183], v[36:39]
	v_mfma_i32_16x16x64_i8 v[32:35], v[164:167], v[180:183], v[32:35]
	v_mfma_i32_16x16x64_i8 v[20:23], v[146:149], v[188:191], v[20:23]
	v_mfma_i32_16x16x64_i8 v[16:19], v[164:167], v[188:191], v[16:19]
	v_mfma_i32_16x16x64_i8 v[4:7], v[146:149], v[210:213], v[4:7]
	v_mfma_i32_16x16x64_i8 v[0:3], v[164:167], v[210:213], v[0:3]
	v_mfma_i32_16x16x64_i8 v[52:55], v[168:171], v[176:179], v[44:47]
	v_mfma_i32_16x16x64_i8 v[36:39], v[160:163], v[184:187], v[36:39]
	v_mfma_i32_16x16x64_i8 v[32:35], v[168:171], v[184:187], v[32:35]
	v_mfma_i32_16x16x64_i8 v[20:23], v[160:163], v[206:209], v[20:23]
	v_mfma_i32_16x16x64_i8 v[16:19], v[168:171], v[206:209], v[16:19]
	v_mfma_i32_16x16x64_i8 v[4:7], v[160:163], v[218:221], v[4:7]
	v_mfma_i32_16x16x64_i8 v[0:3], v[168:171], v[218:221], v[0:3]
	s_setprio 0
	s_barrier
	s_add_i32 s33, s33, 2
	s_add_u32 s18, s18, 0x100
	s_addc_u32 s19, s19, 0
	s_add_u32 s27, s27, 0x100
	s_addc_u32 s29, s29, 0
	s_cmp_gt_u32 s33, 5
	s_cbranch_scc0 .LBB0_328
	s_and_b64 vcc, exec, s[12:13]
	s_cbranch_vccz .LBB0_331
	s_barrier

; #define PG8_STAGE(bufoff, gbase, voff) do { _Pragma("unroll") for (int _i = 0; _i < 2; ++_i) \
;         __builtin_amdgcn_global_load_lds((const unsigned*)((const char*)(gbase) + (voff)[_i]), (PG8_LAS unsigned*)(lds + (bufoff) + ldsw + _i * 8192), 16, 0, 0); } while (0)
; #define PG8_LDA(dst, b, h) do { _Pragma("unroll") for (int m = 0; m < 4; ++m) _Pragma("unroll") for (int k = 0; k < 2; ++k) dst[m][k] = *(const PG8_LAS bf16x8*)(lds + PG8_SA(b, h) + aoff + m * 2048 + k * 1024); } while (0)
; #define PG8_LDB(dst, b, h) do { _Pragma("unroll") for (int n = 0; n < 2; ++n) _Pragma("unroll") for (int k = 0; k < 2; ++k) dst[n][k] = *(const PG8_LAS bf16x8*)(lds + PG8_SB(b, h) + boff + n * 2048 + k * 1024); } while (0)
; #define PG8_WAIT_V(n) asm volatile("s_waitcnt vmcnt(" #n ")" ::: "memory")
; #define PG8_WAIT_L(n) asm volatile("s_waitcnt lgkmcnt(" #n ")" ::: "memory")
; #define PG8_BAR __builtin_amdgcn_s_barrier()
; #define PG8_SCHED __builtin_amdgcn_sched_barrier(0)
;     ...
;             PG8_LDB(B0, 0, 0); PG8_LDB(B1, 0, 1); PG8_SCHED; PG8_LDA(At, 0, 0); PG8_STAGE(PG8_SA(1, 1), a1 + hstepA, voffA);
;             PG8_WAIT_V(8); PG8_WAIT_L(0); PG8_BAR; PG8_MMA(0, 0, At, B0); PG8_MMA(0, 1, At, B1); PG8_BAR; PG8_SCHED;
;             PG8_LDA(At, 0, 1); PG8_STAGE(PG8_SB(0, 0), b2, voffB); PG8_STAGE(PG8_SB(0, 1), b2 + hstepB, voffB); PG8_STAGE(PG8_SA(0, 0), a2, voffA);
;             PG8_WAIT_V(8); PG8_WAIT_L(0); PG8_BAR; PG8_MMA(1, 0, At, B0); PG8_MMA(1, 1, At, B1); PG8_BAR; PG8_SCHED;
.LBB0_734:
	s_add_u32 s30, s28, 0xfffe0080
	s_addc_u32 s31, s29, -1
	s_add_i32 s53, 0, 0x10000
	s_cmp_eq_u32 s52, 4
	s_cselect_b32 s35, s19, s31
	s_cselect_b32 s34, s21, s30
	s_cselect_b32 s31, s15, s33
	s_cselect_b32 s30, s26, s27
	s_add_i32 s56, 0, 0x14000
	v_add_u32_e32 v94, s53, v158
	v_add_u32_e32 v172, s56, v158
	ds_read_b128 v[74:77], v94
	ds_read_b128 v[82:85], v94 offset:1024
	ds_read_b128 v[86:89], v94 offset:2048
	ds_read_b128 v[94:97], v94 offset:3072
	ds_read_b128 v[160:163], v172
	ds_read_b128 v[164:167], v172 offset:1024
	ds_read_b128 v[168:171], v172 offset:2048
	ds_read_b128 v[172:175], v172 offset:3072
	v_lshl_add_u64 v[222:223], s[28:29], 0, v[152:153]
	s_add_i32 m0, s44, 0xc000
	ds_read_b128 v[176:179], v159
	ds_read_b128 v[180:183], v159 offset:1024
	ds_read_b128 v[184:187], v159 offset:2048
	ds_read_b128 v[188:191], v159 offset:3072
	ds_read_b128 v[206:209], v159 offset:4096
	ds_read_b128 v[210:213], v159 offset:5120
	ds_read_b128 v[214:217], v159 offset:6144
	ds_read_b128 v[218:221], v159 offset:7168
	global_load_lds_dwordx4 v[222:223], off
	v_lshl_add_u64 v[222:223], s[28:29], 0, v[154:155]
	s_add_i32 m0, s44, 0xe000
	s_nop 0
	global_load_lds_dwordx4 v[222:223], off
	s_waitcnt vmcnt(8)
	s_waitcnt lgkmcnt(0)
	s_barrier
	s_setprio 1
	s_waitcnt lgkmcnt(0)
	v_mfma_i32_16x16x64_i8 v[142:145], v[74:77], v[176:179], v[142:145]
	v_mfma_i32_16x16x64_i8 v[138:141], v[86:89], v[176:179], v[138:141]
	v_mfma_i32_16x16x64_i8 v[126:129], v[74:77], v[184:187], v[126:129]
	v_mfma_i32_16x16x64_i8 v[122:125], v[86:89], v[184:187], v[122:125]
	v_mfma_i32_16x16x64_i8 v[110:113], v[74:77], v[206:209], v[110:113]
	v_mfma_i32_16x16x64_i8 v[106:109], v[86:89], v[206:209], v[106:109]
	v_mfma_i32_16x16x64_i8 v[90:93], v[74:77], v[214:217], v[90:93]
	v_mfma_i32_16x16x64_i8 v[78:81], v[86:89], v[214:217], v[78:81]
	v_mfma_i32_16x16x64_i8 v[142:145], v[82:85], v[180:183], v[142:145]
	v_mfma_i32_16x16x64_i8 v[138:141], v[94:97], v[180:183], v[138:141]
	v_mfma_i32_16x16x64_i8 v[126:129], v[82:85], v[188:191], v[126:129]
	v_mfma_i32_16x16x64_i8 v[122:125], v[94:97], v[188:191], v[122:125]
	v_mfma_i32_16x16x64_i8 v[110:113], v[82:85], v[210:213], v[110:113]
	v_mfma_i32_16x16x64_i8 v[106:109], v[94:97], v[210:213], v[106:109]
	v_mfma_i32_16x16x64_i8 v[90:93], v[82:85], v[218:221], v[90:93]
	v_mfma_i32_16x16x64_i8 v[78:81], v[94:97], v[218:221], v[78:81]
	v_mfma_i32_16x16x64_i8 v[134:137], v[160:163], v[176:179], v[134:137]
	v_mfma_i32_16x16x64_i8 v[130:133], v[168:171], v[176:179], v[130:133]
	v_mfma_i32_16x16x64_i8 v[118:121], v[160:163], v[184:187], v[118:121]
	v_mfma_i32_16x16x64_i8 v[114:117], v[168:171], v[184:187], v[114:117]
	v_mfma_i32_16x16x64_i8 v[102:105], v[160:163], v[206:209], v[102:105]
	v_mfma_i32_16x16x64_i8 v[98:101], v[168:171], v[206:209], v[98:101]
	v_mfma_i32_16x16x64_i8 v[70:73], v[160:163], v[214:217], v[70:73]
	v_mfma_i32_16x16x64_i8 v[66:69], v[168:171], v[214:217], v[66:69]
	v_mfma_i32_16x16x64_i8 v[134:137], v[164:167], v[180:183], v[134:137]
	v_mfma_i32_16x16x64_i8 v[130:133], v[172:175], v[180:183], v[130:133]
	v_mfma_i32_16x16x64_i8 v[118:121], v[164:167], v[188:191], v[118:121]
	v_mfma_i32_16x16x64_i8 v[114:117], v[172:175], v[188:191], v[114:117]
	v_mfma_i32_16x16x64_i8 v[102:105], v[164:167], v[210:213], v[102:105]
	v_mfma_i32_16x16x64_i8 v[98:101], v[172:175], v[210:213], v[98:101]
	v_mfma_i32_16x16x64_i8 v[70:73], v[164:167], v[218:221], v[70:73]
	v_mfma_i32_16x16x64_i8 v[66:69], v[172:175], v[218:221], v[66:69]
	s_setprio 0
	s_barrier
	s_add_i32 s53, s53, s41
	v_lshl_add_u64 v[222:223], s[30:31], 0, v[64:65]
	s_mov_b32 m0, s53
	ds_read_b128 v[176:179], v159 offset:16384
	ds_read_b128 v[180:183], v159 offset:17408
	ds_read_b128 v[184:187], v159 offset:18432
	ds_read_b128 v[188:191], v159 offset:19456
	ds_read_b128 v[206:209], v159 offset:20480
	ds_read_b128 v[210:213], v159 offset:21504
	ds_read_b128 v[214:217], v159 offset:22528
	ds_read_b128 v[218:221], v159 offset:23552
	global_load_lds_dwordx4 v[222:223], off
	s_add_i32 m0, s53, 0x2000
	s_add_u32 s54, s30, 0x20000
	v_lshl_add_u64 v[224:225], s[30:31], 0, v[146:147]
	s_addc_u32 s55, s31, 0
	s_add_i32 s53, s56, s41
	global_load_lds_dwordx4 v[224:225], off
	v_lshl_add_u64 v[226:227], s[54:55], 0, v[64:65]
	s_mov_b32 m0, s53
	v_lshl_add_u64 v[228:229], s[34:35], 0, v[148:149]
	global_load_lds_dwordx4 v[226:227], off
	v_lshl_add_u64 v[226:227], s[54:55], 0, v[146:147]
	s_add_i32 m0, s53, 0x2000
	s_nop 0
	global_load_lds_dwordx4 v[226:227], off
	v_lshl_add_u64 v[226:227], s[34:35], 0, v[150:151]
	s_mov_b32 m0, s44
	s_nop 0
	global_load_lds_dwordx4 v[226:227], off
	s_mov_b32 m0, s45
	s_nop 0
	global_load_lds_dwordx4 v[228:229], off
	s_waitcnt vmcnt(8)
	s_waitcnt lgkmcnt(0)
	s_barrier
; #define PG8_STAGE(bufoff, gbase, voff) do { _Pragma("unroll") for (int _i = 0; _i < 2; ++_i) \
;         __builtin_amdgcn_global_load_lds((const unsigned*)((const char*)(gbase) + (voff)[_i]), (PG8_LAS unsigned*)(lds + (bufoff) + ldsw + _i * 8192), 16, 0, 0); } while (0)
; #define PG8_LDA(dst, b, h) do { _Pragma("unroll") for (int m = 0; m < 4; ++m) _Pragma("unroll") for (int k = 0; k < 2; ++k) dst[m][k] = *(const PG8_LAS bf16x8*)(lds + PG8_SA(b, h) + aoff + m * 2048 + k * 1024); } while (0)
; #define PG8_LDB(dst, b, h) do { _Pragma("unroll") for (int n = 0; n < 2; ++n) _Pragma("unroll") for (int k = 0; k < 2; ++k) dst[n][k] = *(const PG8_LAS bf16x8*)(lds + PG8_SB(b, h) + boff + n * 2048 + k * 1024); } while (0)
; #define PG8_WAIT_V(n) asm volatile("s_waitcnt vmcnt(" #n ")" ::: "memory")
; #define PG8_WAIT_L(n) asm volatile("s_waitcnt lgkmcnt(" #n ")" ::: "memory")
; #define PG8_BAR __builtin_amdgcn_s_barrier()
; #define PG8_SCHED __builtin_amdgcn_sched_barrier(0)
;     ...
;             PG8_WAIT_V(8); PG8_WAIT_L(0); PG8_BAR; PG8_MMA(1, 0, At, B0); PG8_MMA(1, 1, At, B1); PG8_BAR; PG8_SCHED;
;             PG8_LDB(B0, 1, 0); PG8_LDB(B1, 1, 1); PG8_SCHED; PG8_LDA(At, 1, 0); PG8_STAGE(PG8_SA(0, 1), a2 + hstepA, voffA);
;             PG8_WAIT_V(8); PG8_WAIT_L(0); PG8_BAR; PG8_MMA(0, 0, At, B0); PG8_MMA(0, 1, At, B1); PG8_BAR; PG8_SCHED;
	s_setprio 1
	s_waitcnt lgkmcnt(0)
	v_mfma_i32_16x16x64_i8 v[60:63], v[74:77], v[176:179], v[60:63]
	v_mfma_i32_16x16x64_i8 v[56:59], v[86:89], v[176:179], v[56:59]
	v_mfma_i32_16x16x64_i8 v[44:47], v[74:77], v[184:187], v[44:47]
	v_mfma_i32_16x16x64_i8 v[40:43], v[86:89], v[184:187], v[40:43]
	v_mfma_i32_16x16x64_i8 v[28:31], v[74:77], v[206:209], v[28:31]
	v_mfma_i32_16x16x64_i8 v[24:27], v[86:89], v[206:209], v[24:27]
	v_mfma_i32_16x16x64_i8 v[12:15], v[74:77], v[214:217], v[12:15]
	v_mfma_i32_16x16x64_i8 v[8:11], v[86:89], v[214:217], v[8:11]
	v_mfma_i32_16x16x64_i8 v[60:63], v[82:85], v[180:183], v[60:63]
	v_mfma_i32_16x16x64_i8 v[56:59], v[94:97], v[180:183], v[56:59]
	v_mfma_i32_16x16x64_i8 v[44:47], v[82:85], v[188:191], v[44:47]
	v_mfma_i32_16x16x64_i8 v[40:43], v[94:97], v[188:191], v[40:43]
	v_mfma_i32_16x16x64_i8 v[28:31], v[82:85], v[210:213], v[28:31]
	v_mfma_i32_16x16x64_i8 v[24:27], v[94:97], v[210:213], v[24:27]
	v_mfma_i32_16x16x64_i8 v[12:15], v[82:85], v[218:221], v[12:15]
	v_mfma_i32_16x16x64_i8 v[8:11], v[94:97], v[218:221], v[8:11]
	v_mfma_i32_16x16x64_i8 v[52:55], v[160:163], v[176:179], v[52:55]
	v_mfma_i32_16x16x64_i8 v[48:51], v[168:171], v[176:179], v[48:51]
	v_mfma_i32_16x16x64_i8 v[36:39], v[160:163], v[184:187], v[36:39]
	v_mfma_i32_16x16x64_i8 v[32:35], v[168:171], v[184:187], v[32:35]
	v_mfma_i32_16x16x64_i8 v[20:23], v[160:163], v[206:209], v[20:23]
	v_mfma_i32_16x16x64_i8 v[16:19], v[168:171], v[206:209], v[16:19]
	v_mfma_i32_16x16x64_i8 v[4:7], v[160:163], v[214:217], v[4:7]
	v_mfma_i32_16x16x64_i8 v[0:3], v[168:171], v[214:217], v[0:3]
	v_mfma_i32_16x16x64_i8 v[52:55], v[164:167], v[180:183], v[52:55]
	v_mfma_i32_16x16x64_i8 v[48:51], v[172:175], v[180:183], v[48:51]
	v_mfma_i32_16x16x64_i8 v[36:39], v[164:167], v[188:191], v[36:39]
	v_mfma_i32_16x16x64_i8 v[32:35], v[172:175], v[188:191], v[32:35]
	v_mfma_i32_16x16x64_i8 v[20:23], v[164:167], v[210:213], v[20:23]
	v_mfma_i32_16x16x64_i8 v[16:19], v[172:175], v[210:213], v[16:19]
	v_mfma_i32_16x16x64_i8 v[4:7], v[164:167], v[218:221], v[4:7]
	v_mfma_i32_16x16x64_i8 v[0:3], v[172:175], v[218:221], v[0:3]
	s_setprio 0
	s_barrier
	s_add_i32 s53, 0, 0x18000
	s_add_i32 s54, 0, 0x1c000
	v_add_u32_e32 v94, s53, v158
	v_add_u32_e32 v172, s54, v158
	ds_read_b128 v[74:77], v94
	ds_read_b128 v[82:85], v94 offset:1024
	ds_read_b128 v[86:89], v94 offset:2048
	ds_read_b128 v[94:97], v94 offset:3072
	ds_read_b128 v[160:163], v172
	ds_read_b128 v[164:167], v172 offset:1024
	ds_read_b128 v[168:171], v172 offset:2048
	ds_read_b128 v[172:175], v172 offset:3072
	s_add_u32 s34, s34, 0x20000
	s_addc_u32 s35, s35, 0
	s_mov_b32 m0, s46
	v_lshl_add_u64 v[230:231], s[34:35], 0, v[150:151]
	ds_read_b128 v[176:179], v159 offset:32768
	ds_read_b128 v[180:183], v159 offset:33792
	ds_read_b128 v[184:187], v159 offset:34816
	ds_read_b128 v[188:191], v159 offset:35840
	ds_read_b128 v[206:209], v159 offset:36864
	ds_read_b128 v[210:213], v159 offset:37888
	ds_read_b128 v[214:217], v159 offset:38912
	ds_read_b128 v[218:221], v159 offset:39936
	global_load_lds_dwordx4 v[230:231], off
	v_lshl_add_u64 v[230:231], s[34:35], 0, v[148:149]
	s_mov_b32 m0, s47
	s_nop 0
	global_load_lds_dwordx4 v[230:231], off
	s_waitcnt vmcnt(8)
	s_waitcnt lgkmcnt(0)
	s_barrier
	s_setprio 1
	s_waitcnt lgkmcnt(0)
	v_mfma_i32_16x16x64_i8 v[142:145], v[74:77], v[176:179], v[142:145]
	v_mfma_i32_16x16x64_i8 v[138:141], v[86:89], v[176:179], v[138:141]
	v_mfma_i32_16x16x64_i8 v[126:129], v[74:77], v[184:187], v[126:129]
	v_mfma_i32_16x16x64_i8 v[122:125], v[86:89], v[184:187], v[122:125]
	v_mfma_i32_16x16x64_i8 v[110:113], v[74:77], v[206:209], v[110:113]
	v_mfma_i32_16x16x64_i8 v[106:109], v[86:89], v[206:209], v[106:109]
	v_mfma_i32_16x16x64_i8 v[90:93], v[74:77], v[214:217], v[90:93]
	v_mfma_i32_16x16x64_i8 v[78:81], v[86:89], v[214:217], v[78:81]
	v_mfma_i32_16x16x64_i8 v[142:145], v[82:85], v[180:183], v[142:145]
	v_mfma_i32_16x16x64_i8 v[138:141], v[94:97], v[180:183], v[138:141]
	v_mfma_i32_16x16x64_i8 v[126:129], v[82:85], v[188:191], v[126:129]
	v_mfma_i32_16x16x64_i8 v[122:125], v[94:97], v[188:191], v[122:125]
	v_mfma_i32_16x16x64_i8 v[110:113], v[82:85], v[210:213], v[110:113]
	v_mfma_i32_16x16x64_i8 v[106:109], v[94:97], v[210:213], v[106:109]
	v_mfma_i32_16x16x64_i8 v[90:93], v[82:85], v[218:221], v[90:93]
	v_mfma_i32_16x16x64_i8 v[78:81], v[94:97], v[218:221], v[78:81]
	v_mfma_i32_16x16x64_i8 v[134:137], v[160:163], v[176:179], v[134:137]
	v_mfma_i32_16x16x64_i8 v[130:133], v[168:171], v[176:179], v[130:133]
	v_mfma_i32_16x16x64_i8 v[118:121], v[160:163], v[184:187], v[118:121]
	v_mfma_i32_16x16x64_i8 v[114:117], v[168:171], v[184:187], v[114:117]
	v_mfma_i32_16x16x64_i8 v[102:105], v[160:163], v[206:209], v[102:105]
	v_mfma_i32_16x16x64_i8 v[98:101], v[168:171], v[206:209], v[98:101]
	v_mfma_i32_16x16x64_i8 v[70:73], v[160:163], v[214:217], v[70:73]
	v_mfma_i32_16x16x64_i8 v[66:69], v[168:171], v[214:217], v[66:69]
	v_mfma_i32_16x16x64_i8 v[134:137], v[164:167], v[180:183], v[134:137]
	v_mfma_i32_16x16x64_i8 v[130:133], v[172:175], v[180:183], v[130:133]
	v_mfma_i32_16x16x64_i8 v[118:121], v[164:167], v[188:191], v[118:121]
	v_mfma_i32_16x16x64_i8 v[114:117], v[172:175], v[188:191], v[114:117]
	v_mfma_i32_16x16x64_i8 v[102:105], v[164:167], v[210:213], v[102:105]
	v_mfma_i32_16x16x64_i8 v[98:101], v[172:175], v[210:213], v[98:101]
	v_mfma_i32_16x16x64_i8 v[70:73], v[164:167], v[218:221], v[70:73]
	v_mfma_i32_16x16x64_i8 v[66:69], v[172:175], v[218:221], v[66:69]
	s_setprio 0
	s_barrier
; #define PG8_STAGE(bufoff, gbase, voff) do { _Pragma("unroll") for (int _i = 0; _i < 2; ++_i) \
;         __builtin_amdgcn_global_load_lds((const unsigned*)((const char*)(gbase) + (voff)[_i]), (PG8_LAS unsigned*)(lds + (bufoff) + ldsw + _i * 8192), 16, 0, 0); } while (0)
; #define PG8_LDA(dst, b, h) do { _Pragma("unroll") for (int m = 0; m < 4; ++m) _Pragma("unroll") for (int k = 0; k < 2; ++k) dst[m][k] = *(const PG8_LAS bf16x8*)(lds + PG8_SA(b, h) + aoff + m * 2048 + k * 1024); } while (0)
; #define PG8_WAIT_V(n) asm volatile("s_waitcnt vmcnt(" #n ")" ::: "memory")
; #define PG8_WAIT_L(n) asm volatile("s_waitcnt lgkmcnt(" #n ")" ::: "memory")
; #define PG8_BAR __builtin_amdgcn_s_barrier()
; #define PG8_SCHED __builtin_amdgcn_sched_barrier(0)
;     ...
;             PG8_WAIT_V(8); PG8_WAIT_L(0); PG8_BAR; PG8_MMA(0, 0, At, B0); PG8_MMA(0, 1, At, B1); PG8_BAR; PG8_SCHED;
;             PG8_LDA(At, 1, 1); PG8_STAGE(PG8_SB(1, 0), b3, voffB); PG8_STAGE(PG8_SB(1, 1), b3 + hstepB, voffB); PG8_STAGE(PG8_SA(1, 0), a3, voffA);
;             PG8_WAIT_V(8); PG8_WAIT_L(0); PG8_BAR; PG8_MMA(1, 0, At, B0); PG8_MMA(1, 1, At, B1); PG8_BAR; PG8_SCHED;
	s_add_i32 s34, s53, s41
	v_lshl_add_u64 v[222:223], v[222:223], 0, s[58:59]
	s_mov_b32 m0, s34
	ds_read_b128 v[176:179], v159 offset:49152
	ds_read_b128 v[180:183], v159 offset:50176
	ds_read_b128 v[184:187], v159 offset:51200
	ds_read_b128 v[188:191], v159 offset:52224
	ds_read_b128 v[206:209], v159 offset:53248
	ds_read_b128 v[210:213], v159 offset:54272
	ds_read_b128 v[214:217], v159 offset:55296
	ds_read_b128 v[218:221], v159 offset:56320
	global_load_lds_dwordx4 v[222:223], off
	s_add_i32 m0, s34, 0x2000
	s_add_u32 s30, s30, 0x20080
	v_lshl_add_u64 v[222:223], v[224:225], 0, s[58:59]
	s_addc_u32 s31, s31, 0
	s_add_i32 s34, s54, s41
	global_load_lds_dwordx4 v[222:223], off
	v_lshl_add_u64 v[222:223], s[30:31], 0, v[64:65]
	s_mov_b32 m0, s34
	s_nop 0
	global_load_lds_dwordx4 v[222:223], off
	v_lshl_add_u64 v[222:223], s[30:31], 0, v[146:147]
	s_add_i32 m0, s34, 0x2000
	s_nop 0
	global_load_lds_dwordx4 v[222:223], off
	v_lshl_add_u64 v[222:223], v[226:227], 0, s[58:59]
	s_mov_b32 m0, s49
	s_nop 0
	global_load_lds_dwordx4 v[222:223], off
	v_lshl_add_u64 v[222:223], v[228:229], 0, s[58:59]
	s_mov_b32 m0, s50
	s_nop 0
	global_load_lds_dwordx4 v[222:223], off
	s_waitcnt vmcnt(8)
	s_waitcnt lgkmcnt(0)
	s_barrier
	s_setprio 1
	s_waitcnt lgkmcnt(0)
	v_mfma_i32_16x16x64_i8 v[60:63], v[74:77], v[176:179], v[60:63]
	v_mfma_i32_16x16x64_i8 v[56:59], v[86:89], v[176:179], v[56:59]
	v_mfma_i32_16x16x64_i8 v[44:47], v[74:77], v[184:187], v[44:47]
	v_mfma_i32_16x16x64_i8 v[40:43], v[86:89], v[184:187], v[40:43]
	v_mfma_i32_16x16x64_i8 v[28:31], v[74:77], v[206:209], v[28:31]
	v_mfma_i32_16x16x64_i8 v[24:27], v[86:89], v[206:209], v[24:27]
	v_mfma_i32_16x16x64_i8 v[12:15], v[74:77], v[214:217], v[12:15]
	v_mfma_i32_16x16x64_i8 v[8:11], v[86:89], v[214:217], v[8:11]
	v_mfma_i32_16x16x64_i8 v[60:63], v[82:85], v[180:183], v[60:63]
	v_mfma_i32_16x16x64_i8 v[56:59], v[94:97], v[180:183], v[56:59]
	v_mfma_i32_16x16x64_i8 v[44:47], v[82:85], v[188:191], v[44:47]
	v_mfma_i32_16x16x64_i8 v[40:43], v[94:97], v[188:191], v[40:43]
	v_mfma_i32_16x16x64_i8 v[28:31], v[82:85], v[210:213], v[28:31]
	v_mfma_i32_16x16x64_i8 v[24:27], v[94:97], v[210:213], v[24:27]
	v_mfma_i32_16x16x64_i8 v[12:15], v[82:85], v[218:221], v[12:15]
	v_mfma_i32_16x16x64_i8 v[8:11], v[94:97], v[218:221], v[8:11]
	v_mfma_i32_16x16x64_i8 v[52:55], v[160:163], v[176:179], v[52:55]
	v_mfma_i32_16x16x64_i8 v[48:51], v[168:171], v[176:179], v[48:51]
	v_mfma_i32_16x16x64_i8 v[36:39], v[160:163], v[184:187], v[36:39]
	v_mfma_i32_16x16x64_i8 v[32:35], v[168:171], v[184:187], v[32:35]
	v_mfma_i32_16x16x64_i8 v[20:23], v[160:163], v[206:209], v[20:23]
	v_mfma_i32_16x16x64_i8 v[16:19], v[168:171], v[206:209], v[16:19]
	v_mfma_i32_16x16x64_i8 v[4:7], v[160:163], v[214:217], v[4:7]
	v_mfma_i32_16x16x64_i8 v[0:3], v[168:171], v[214:217], v[0:3]
	v_mfma_i32_16x16x64_i8 v[52:55], v[164:167], v[180:183], v[52:55]
	v_mfma_i32_16x16x64_i8 v[48:51], v[172:175], v[180:183], v[48:51]
	v_mfma_i32_16x16x64_i8 v[36:39], v[164:167], v[188:191], v[36:39]
	v_mfma_i32_16x16x64_i8 v[32:35], v[172:175], v[188:191], v[32:35]
	v_mfma_i32_16x16x64_i8 v[20:23], v[164:167], v[210:213], v[20:23]
	v_mfma_i32_16x16x64_i8 v[16:19], v[172:175], v[210:213], v[16:19]
	v_mfma_i32_16x16x64_i8 v[4:7], v[164:167], v[218:221], v[4:7]
	v_mfma_i32_16x16x64_i8 v[0:3], v[172:175], v[218:221], v[0:3]
	s_setprio 0
	s_barrier
	s_add_i32 s52, s52, 2
	s_add_u32 s28, s28, 0x100
	s_addc_u32 s29, s29, 0
	s_add_u32 s27, s27, 0x100
	s_addc_u32 s33, s33, 0
	s_cmp_gt_u32 s52, 5
	s_cbranch_scc0 .LBB0_734
	s_and_b64 vcc, exec, s[12:13]
	s_cbranch_vccz .LBB0_737
	s_barrier

; #define PG8_STAGE(bufoff, gbase, voff) do { _Pragma("unroll") for (int _i = 0; _i < 2; ++_i) \
;         __builtin_amdgcn_global_load_lds((const unsigned*)((const char*)(gbase) + (voff)[_i]), (PG8_LAS unsigned*)(lds + (bufoff) + ldsw + _i * 8192), 16, 0, 0); } while (0)
; #define PG8_LDA(dst, b, h) do { _Pragma("unroll") for (int m = 0; m < 4; ++m) _Pragma("unroll") for (int k = 0; k < 2; ++k) dst[m][k] = *(const PG8_LAS bf16x8*)(lds + PG8_SA(b, h) + aoff + m * 2048 + k * 1024); } while (0)
; #define PG8_LDB(dst, b, h) do { _Pragma("unroll") for (int n = 0; n < 2; ++n) _Pragma("unroll") for (int k = 0; k < 2; ++k) dst[n][k] = *(const PG8_LAS bf16x8*)(lds + PG8_SB(b, h) + boff + n * 2048 + k * 1024); } while (0)
; #define PG8_WAIT_V(n) asm volatile("s_waitcnt vmcnt(" #n ")" ::: "memory")
; #define PG8_WAIT_L(n) asm volatile("s_waitcnt lgkmcnt(" #n ")" ::: "memory")
; #define PG8_BAR __builtin_amdgcn_s_barrier()
; #define PG8_SCHED __builtin_amdgcn_sched_barrier(0)
;     ...
;             PG8_LDB(B0, 0, 0); PG8_LDB(B1, 0, 1); PG8_SCHED; PG8_LDA(At, 0, 0); PG8_STAGE(PG8_SA(1, 1), a1 + hstepA, voffA);
;             PG8_WAIT_V(8); PG8_WAIT_L(0); PG8_BAR; PG8_MMA(0, 0, At, B0); PG8_MMA(0, 1, At, B1); PG8_BAR; PG8_SCHED;
;             PG8_LDA(At, 0, 1); PG8_STAGE(PG8_SB(0, 0), b2, voffB); PG8_STAGE(PG8_SB(0, 1), b2 + hstepB, voffB); PG8_STAGE(PG8_SA(0, 0), a2, voffA);
;             PG8_WAIT_V(8); PG8_WAIT_L(0); PG8_BAR; PG8_MMA(1, 0, At, B0); PG8_MMA(1, 1, At, B1); PG8_BAR; PG8_SCHED;
.LBB0_759:
	s_add_i32 s41, s24, 2
	s_add_u32 s53, s22, 0x80
	s_addc_u32 s25, s23, 0
	s_add_i32 s56, 0, 0x10000
	s_cmp_eq_u32 s26, s24
	s_cselect_b32 s25, s15, s25
	s_cselect_b32 s24, s14, s53
	s_cselect_b32 s55, s19, s40
	s_cselect_b32 s54, s18, s21
	s_add_i32 s53, 0, 0x14000
	v_add_u32_e32 v156, s56, v142
	v_add_u32_e32 v172, s53, v142
	ds_read_b128 v[144:147], v156
	ds_read_b128 v[148:151], v156 offset:1024
	ds_read_b128 v[152:155], v156 offset:2048
	ds_read_b128 v[156:159], v156 offset:3072
	ds_read_b128 v[160:163], v172
	ds_read_b128 v[164:167], v172 offset:1024
	ds_read_b128 v[168:171], v172 offset:2048
	ds_read_b128 v[172:175], v172 offset:3072
	v_lshl_add_u64 v[222:223], s[22:23], 0, v[136:137]
	s_add_i32 m0, s31, 0xc000
	ds_read_b128 v[176:179], v143
	ds_read_b128 v[180:183], v143 offset:1024
	ds_read_b128 v[184:187], v143 offset:2048
	ds_read_b128 v[188:191], v143 offset:3072
	ds_read_b128 v[206:209], v143 offset:4096
	ds_read_b128 v[210:213], v143 offset:5120
	ds_read_b128 v[214:217], v143 offset:6144
	ds_read_b128 v[218:221], v143 offset:7168
	global_load_lds_dwordx4 v[222:223], off
	v_lshl_add_u64 v[222:223], s[22:23], 0, v[138:139]
	s_add_i32 m0, s31, 0xe000
	s_nop 0
	global_load_lds_dwordx4 v[222:223], off
	s_waitcnt vmcnt(8)
	s_waitcnt lgkmcnt(0)
	s_barrier
	s_setprio 1
	s_waitcnt lgkmcnt(0)
	v_mfma_f32_16x16x32_bf16 v[122:125], v[144:147], v[176:179], v[122:125]
	v_mfma_f32_16x16x32_bf16 v[126:129], v[152:155], v[176:179], v[126:129]
	v_mfma_f32_16x16x32_bf16 v[110:113], v[144:147], v[184:187], v[110:113]
	v_mfma_f32_16x16x32_bf16 v[106:109], v[152:155], v[184:187], v[106:109]
	v_mfma_f32_16x16x32_bf16 v[94:97], v[144:147], v[206:209], v[94:97]
	v_mfma_f32_16x16x32_bf16 v[90:93], v[152:155], v[206:209], v[90:93]
	v_mfma_f32_16x16x32_bf16 v[78:81], v[144:147], v[214:217], v[78:81]
	v_mfma_f32_16x16x32_bf16 v[74:77], v[152:155], v[214:217], v[74:77]
	v_mfma_f32_16x16x32_bf16 v[122:125], v[148:151], v[180:183], v[122:125]
	v_mfma_f32_16x16x32_bf16 v[126:129], v[156:159], v[180:183], v[126:129]
	v_mfma_f32_16x16x32_bf16 v[110:113], v[148:151], v[188:191], v[110:113]
	v_mfma_f32_16x16x32_bf16 v[106:109], v[156:159], v[188:191], v[106:109]
	v_mfma_f32_16x16x32_bf16 v[94:97], v[148:151], v[210:213], v[94:97]
	v_mfma_f32_16x16x32_bf16 v[90:93], v[156:159], v[210:213], v[90:93]
	v_mfma_f32_16x16x32_bf16 v[78:81], v[148:151], v[218:221], v[78:81]
	v_mfma_f32_16x16x32_bf16 v[74:77], v[156:159], v[218:221], v[74:77]
	v_mfma_f32_16x16x32_bf16 v[118:121], v[160:163], v[176:179], v[118:121]
	v_mfma_f32_16x16x32_bf16 v[114:117], v[168:171], v[176:179], v[114:117]
	v_mfma_f32_16x16x32_bf16 v[102:105], v[160:163], v[184:187], v[102:105]
	v_mfma_f32_16x16x32_bf16 v[98:101], v[168:171], v[184:187], v[98:101]
	v_mfma_f32_16x16x32_bf16 v[86:89], v[160:163], v[206:209], v[86:89]
	v_mfma_f32_16x16x32_bf16 v[82:85], v[168:171], v[206:209], v[82:85]
	v_mfma_f32_16x16x32_bf16 v[70:73], v[160:163], v[214:217], v[70:73]
	v_mfma_f32_16x16x32_bf16 v[66:69], v[168:171], v[214:217], v[66:69]
	v_mfma_f32_16x16x32_bf16 v[118:121], v[164:167], v[180:183], v[118:121]
	v_mfma_f32_16x16x32_bf16 v[114:117], v[172:175], v[180:183], v[114:117]
	v_mfma_f32_16x16x32_bf16 v[102:105], v[164:167], v[188:191], v[102:105]
	v_mfma_f32_16x16x32_bf16 v[98:101], v[172:175], v[188:191], v[98:101]
	v_mfma_f32_16x16x32_bf16 v[86:89], v[164:167], v[210:213], v[86:89]
	v_mfma_f32_16x16x32_bf16 v[82:85], v[172:175], v[210:213], v[82:85]
	v_mfma_f32_16x16x32_bf16 v[70:73], v[164:167], v[218:221], v[70:73]
	v_mfma_f32_16x16x32_bf16 v[66:69], v[172:175], v[218:221], v[66:69]
	s_setprio 0
	s_barrier
	s_add_i32 s56, s56, s30
	v_lshl_add_u64 v[222:223], s[54:55], 0, v[64:65]
	s_mov_b32 m0, s56
	ds_read_b128 v[176:179], v143 offset:16384
	ds_read_b128 v[180:183], v143 offset:17408
	ds_read_b128 v[184:187], v143 offset:18432
	ds_read_b128 v[188:191], v143 offset:19456
	ds_read_b128 v[206:209], v143 offset:20480
	ds_read_b128 v[210:213], v143 offset:21504
	ds_read_b128 v[214:217], v143 offset:22528
	ds_read_b128 v[218:221], v143 offset:23552
	global_load_lds_dwordx4 v[222:223], off
	s_add_i32 m0, s56, 0x2000
	v_lshl_add_u64 v[224:225], s[54:55], 0, v[130:131]
	s_add_u32 s54, s54, s0
	s_addc_u32 s55, s55, s1
	s_add_i32 s53, s53, s30
	global_load_lds_dwordx4 v[224:225], off
	v_lshl_add_u64 v[226:227], s[54:55], 0, v[64:65]
	s_mov_b32 m0, s53
	v_lshl_add_u64 v[228:229], s[54:55], 0, v[130:131]
	global_load_lds_dwordx4 v[226:227], off
	s_add_i32 m0, s53, 0x2000
	v_lshl_add_u64 v[230:231], s[24:25], 0, v[134:135]
	global_load_lds_dwordx4 v[228:229], off
	s_mov_b32 m0, s31
	v_lshl_add_u64 v[238:239], s[24:25], 0, v[132:133]
	global_load_lds_dwordx4 v[230:231], off
	s_mov_b32 m0, s10
	s_nop 0
	global_load_lds_dwordx4 v[238:239], off
	s_waitcnt vmcnt(8)
	s_waitcnt lgkmcnt(0)
	s_barrier
; #define PG8_STAGE(bufoff, gbase, voff) do { _Pragma("unroll") for (int _i = 0; _i < 2; ++_i) \
;         __builtin_amdgcn_global_load_lds((const unsigned*)((const char*)(gbase) + (voff)[_i]), (PG8_LAS unsigned*)(lds + (bufoff) + ldsw + _i * 8192), 16, 0, 0); } while (0)
; #define PG8_LDA(dst, b, h) do { _Pragma("unroll") for (int m = 0; m < 4; ++m) _Pragma("unroll") for (int k = 0; k < 2; ++k) dst[m][k] = *(const PG8_LAS bf16x8*)(lds + PG8_SA(b, h) + aoff + m * 2048 + k * 1024); } while (0)
; #define PG8_LDB(dst, b, h) do { _Pragma("unroll") for (int n = 0; n < 2; ++n) _Pragma("unroll") for (int k = 0; k < 2; ++k) dst[n][k] = *(const PG8_LAS bf16x8*)(lds + PG8_SB(b, h) + boff + n * 2048 + k * 1024); } while (0)
; #define PG8_WAIT_V(n) asm volatile("s_waitcnt vmcnt(" #n ")" ::: "memory")
; #define PG8_WAIT_L(n) asm volatile("s_waitcnt lgkmcnt(" #n ")" ::: "memory")
; #define PG8_BAR __builtin_amdgcn_s_barrier()
; #define PG8_SCHED __builtin_amdgcn_sched_barrier(0)
;     ...
;             PG8_WAIT_V(8); PG8_WAIT_L(0); PG8_BAR; PG8_MMA(1, 0, At, B0); PG8_MMA(1, 1, At, B1); PG8_BAR; PG8_SCHED;
;             PG8_LDB(B0, 1, 0); PG8_LDB(B1, 1, 1); PG8_SCHED; PG8_LDA(At, 1, 0); PG8_STAGE(PG8_SA(0, 1), a2 + hstepA, voffA);
;             PG8_WAIT_V(8); PG8_WAIT_L(0); PG8_BAR; PG8_MMA(0, 0, At, B0); PG8_MMA(0, 1, At, B1); PG8_BAR; PG8_SCHED;
	s_setprio 1
	s_waitcnt lgkmcnt(0)
	v_mfma_f32_16x16x32_bf16 v[60:63], v[144:147], v[176:179], v[60:63]
	v_mfma_f32_16x16x32_bf16 v[56:59], v[152:155], v[176:179], v[56:59]
	v_mfma_f32_16x16x32_bf16 v[44:47], v[144:147], v[184:187], v[44:47]
	v_mfma_f32_16x16x32_bf16 v[40:43], v[152:155], v[184:187], v[40:43]
	v_mfma_f32_16x16x32_bf16 v[28:31], v[144:147], v[206:209], v[28:31]
	v_mfma_f32_16x16x32_bf16 v[24:27], v[152:155], v[206:209], v[24:27]
	v_mfma_f32_16x16x32_bf16 v[12:15], v[144:147], v[214:217], v[12:15]
	v_mfma_f32_16x16x32_bf16 v[8:11], v[152:155], v[214:217], v[8:11]
	v_mfma_f32_16x16x32_bf16 v[60:63], v[148:151], v[180:183], v[60:63]
	v_mfma_f32_16x16x32_bf16 v[56:59], v[156:159], v[180:183], v[56:59]
	v_mfma_f32_16x16x32_bf16 v[44:47], v[148:151], v[188:191], v[44:47]
	v_mfma_f32_16x16x32_bf16 v[40:43], v[156:159], v[188:191], v[40:43]
	v_mfma_f32_16x16x32_bf16 v[28:31], v[148:151], v[210:213], v[28:31]
	v_mfma_f32_16x16x32_bf16 v[24:27], v[156:159], v[210:213], v[24:27]
	v_mfma_f32_16x16x32_bf16 v[12:15], v[148:151], v[218:221], v[12:15]
	v_mfma_f32_16x16x32_bf16 v[8:11], v[156:159], v[218:221], v[8:11]
	v_mfma_f32_16x16x32_bf16 v[52:55], v[160:163], v[176:179], v[52:55]
	v_mfma_f32_16x16x32_bf16 v[48:51], v[168:171], v[176:179], v[48:51]
	v_mfma_f32_16x16x32_bf16 v[36:39], v[160:163], v[184:187], v[36:39]
	v_mfma_f32_16x16x32_bf16 v[32:35], v[168:171], v[184:187], v[32:35]
	v_mfma_f32_16x16x32_bf16 v[20:23], v[160:163], v[206:209], v[20:23]
	v_mfma_f32_16x16x32_bf16 v[16:19], v[168:171], v[206:209], v[16:19]
	v_mfma_f32_16x16x32_bf16 v[4:7], v[160:163], v[214:217], v[4:7]
	v_mfma_f32_16x16x32_bf16 v[0:3], v[168:171], v[214:217], v[0:3]
	v_mfma_f32_16x16x32_bf16 v[52:55], v[164:167], v[180:183], v[52:55]
	v_mfma_f32_16x16x32_bf16 v[48:51], v[172:175], v[180:183], v[48:51]
	v_mfma_f32_16x16x32_bf16 v[36:39], v[164:167], v[188:191], v[36:39]
	v_mfma_f32_16x16x32_bf16 v[32:35], v[172:175], v[188:191], v[32:35]
	v_mfma_f32_16x16x32_bf16 v[20:23], v[164:167], v[210:213], v[20:23]
	v_mfma_f32_16x16x32_bf16 v[16:19], v[172:175], v[210:213], v[16:19]
	v_mfma_f32_16x16x32_bf16 v[4:7], v[164:167], v[218:221], v[4:7]
	v_mfma_f32_16x16x32_bf16 v[0:3], v[172:175], v[218:221], v[0:3]
	s_setprio 0
	s_barrier
	s_add_i32 s53, 0, 0x18000
	s_add_i32 s54, 0, 0x1c000
	v_add_u32_e32 v156, s53, v142
	v_add_u32_e32 v172, s54, v142
	ds_read_b128 v[144:147], v156
	ds_read_b128 v[148:151], v156 offset:1024
	ds_read_b128 v[152:155], v156 offset:2048
	ds_read_b128 v[156:159], v156 offset:3072
	ds_read_b128 v[160:163], v172
	ds_read_b128 v[164:167], v172 offset:1024
	ds_read_b128 v[168:171], v172 offset:2048
	ds_read_b128 v[172:175], v172 offset:3072
	s_add_u32 s24, s24, s0
	s_addc_u32 s25, s25, s1
	s_mov_b32 m0, s11
	v_lshl_add_u64 v[242:243], s[24:25], 0, v[134:135]
	ds_read_b128 v[176:179], v143 offset:32768
	ds_read_b128 v[180:183], v143 offset:33792
	ds_read_b128 v[184:187], v143 offset:34816
	ds_read_b128 v[188:191], v143 offset:35840
	ds_read_b128 v[206:209], v143 offset:36864
	ds_read_b128 v[210:213], v143 offset:37888
	ds_read_b128 v[214:217], v143 offset:38912
	ds_read_b128 v[218:221], v143 offset:39936
	global_load_lds_dwordx4 v[242:243], off
	v_lshl_add_u64 v[242:243], s[24:25], 0, v[132:133]
	s_mov_b32 m0, s34
	s_nop 0
	global_load_lds_dwordx4 v[242:243], off
	s_waitcnt vmcnt(8)
	s_waitcnt lgkmcnt(0)
	s_barrier
	s_setprio 1
	s_waitcnt lgkmcnt(0)
	v_mfma_f32_16x16x32_bf16 v[122:125], v[144:147], v[176:179], v[122:125]
	v_mfma_f32_16x16x32_bf16 v[126:129], v[152:155], v[176:179], v[126:129]
	v_mfma_f32_16x16x32_bf16 v[110:113], v[144:147], v[184:187], v[110:113]
	v_mfma_f32_16x16x32_bf16 v[106:109], v[152:155], v[184:187], v[106:109]
	v_mfma_f32_16x16x32_bf16 v[94:97], v[144:147], v[206:209], v[94:97]
	v_mfma_f32_16x16x32_bf16 v[90:93], v[152:155], v[206:209], v[90:93]
	v_mfma_f32_16x16x32_bf16 v[78:81], v[144:147], v[214:217], v[78:81]
	v_mfma_f32_16x16x32_bf16 v[74:77], v[152:155], v[214:217], v[74:77]
	v_mfma_f32_16x16x32_bf16 v[122:125], v[148:151], v[180:183], v[122:125]
	v_mfma_f32_16x16x32_bf16 v[126:129], v[156:159], v[180:183], v[126:129]
	v_mfma_f32_16x16x32_bf16 v[110:113], v[148:151], v[188:191], v[110:113]
	v_mfma_f32_16x16x32_bf16 v[106:109], v[156:159], v[188:191], v[106:109]
	v_mfma_f32_16x16x32_bf16 v[94:97], v[148:151], v[210:213], v[94:97]
	v_mfma_f32_16x16x32_bf16 v[90:93], v[156:159], v[210:213], v[90:93]
	v_mfma_f32_16x16x32_bf16 v[78:81], v[148:151], v[218:221], v[78:81]
	v_mfma_f32_16x16x32_bf16 v[74:77], v[156:159], v[218:221], v[74:77]
	v_mfma_f32_16x16x32_bf16 v[118:121], v[160:163], v[176:179], v[118:121]
	v_mfma_f32_16x16x32_bf16 v[114:117], v[168:171], v[176:179], v[114:117]
	v_mfma_f32_16x16x32_bf16 v[102:105], v[160:163], v[184:187], v[102:105]
	v_mfma_f32_16x16x32_bf16 v[98:101], v[168:171], v[184:187], v[98:101]
	v_mfma_f32_16x16x32_bf16 v[86:89], v[160:163], v[206:209], v[86:89]
	v_mfma_f32_16x16x32_bf16 v[82:85], v[168:171], v[206:209], v[82:85]
	v_mfma_f32_16x16x32_bf16 v[70:73], v[160:163], v[214:217], v[70:73]
	v_mfma_f32_16x16x32_bf16 v[66:69], v[168:171], v[214:217], v[66:69]
	v_mfma_f32_16x16x32_bf16 v[118:121], v[164:167], v[180:183], v[118:121]
	v_mfma_f32_16x16x32_bf16 v[114:117], v[172:175], v[180:183], v[114:117]
	v_mfma_f32_16x16x32_bf16 v[102:105], v[164:167], v[188:191], v[102:105]
	v_mfma_f32_16x16x32_bf16 v[98:101], v[172:175], v[188:191], v[98:101]
	v_mfma_f32_16x16x32_bf16 v[86:89], v[164:167], v[210:213], v[86:89]
	v_mfma_f32_16x16x32_bf16 v[82:85], v[172:175], v[210:213], v[82:85]
	v_mfma_f32_16x16x32_bf16 v[70:73], v[164:167], v[218:221], v[70:73]
	v_mfma_f32_16x16x32_bf16 v[66:69], v[172:175], v[218:221], v[66:69]
	s_setprio 0
	s_barrier
; #define PG8_STAGE(bufoff, gbase, voff) do { _Pragma("unroll") for (int _i = 0; _i < 2; ++_i) \
;         __builtin_amdgcn_global_load_lds((const unsigned*)((const char*)(gbase) + (voff)[_i]), (PG8_LAS unsigned*)(lds + (bufoff) + ldsw + _i * 8192), 16, 0, 0); } while (0)
; #define PG8_LDA(dst, b, h) do { _Pragma("unroll") for (int m = 0; m < 4; ++m) _Pragma("unroll") for (int k = 0; k < 2; ++k) dst[m][k] = *(const PG8_LAS bf16x8*)(lds + PG8_SA(b, h) + aoff + m * 2048 + k * 1024); } while (0)
; #define PG8_WAIT_V(n) asm volatile("s_waitcnt vmcnt(" #n ")" ::: "memory")
; #define PG8_WAIT_L(n) asm volatile("s_waitcnt lgkmcnt(" #n ")" ::: "memory")
; #define PG8_BAR __builtin_amdgcn_s_barrier()
; #define PG8_SCHED __builtin_amdgcn_sched_barrier(0)
;     ...
;             PG8_WAIT_V(8); PG8_WAIT_L(0); PG8_BAR; PG8_MMA(0, 0, At, B0); PG8_MMA(0, 1, At, B1); PG8_BAR; PG8_SCHED;
;             PG8_LDA(At, 1, 1); PG8_STAGE(PG8_SB(1, 0), b3, voffB); PG8_STAGE(PG8_SB(1, 1), b3 + hstepB, voffB); PG8_STAGE(PG8_SA(1, 0), a3, voffA);
;             PG8_WAIT_V(8); PG8_WAIT_L(0); PG8_BAR; PG8_MMA(1, 0, At, B0); PG8_MMA(1, 1, At, B1); PG8_BAR; PG8_SCHED;
	s_add_i32 s24, s53, s30
	v_lshl_add_u64 v[222:223], v[222:223], 0, s[58:59]
	s_mov_b32 m0, s24
	ds_read_b128 v[176:179], v143 offset:49152
	ds_read_b128 v[180:183], v143 offset:50176
	ds_read_b128 v[184:187], v143 offset:51200
	ds_read_b128 v[188:191], v143 offset:52224
	ds_read_b128 v[206:209], v143 offset:53248
	ds_read_b128 v[210:213], v143 offset:54272
	ds_read_b128 v[214:217], v143 offset:55296
	ds_read_b128 v[218:221], v143 offset:56320
	global_load_lds_dwordx4 v[222:223], off
	v_lshl_add_u64 v[222:223], v[224:225], 0, s[58:59]
	s_add_i32 m0, s24, 0x2000
	s_add_i32 s24, s54, s30
	global_load_lds_dwordx4 v[222:223], off
	v_lshl_add_u64 v[222:223], v[226:227], 0, s[58:59]
	s_mov_b32 m0, s24
	s_nop 0
	global_load_lds_dwordx4 v[222:223], off
	v_lshl_add_u64 v[222:223], v[228:229], 0, s[58:59]
	s_add_i32 m0, s24, 0x2000
	s_nop 0
	global_load_lds_dwordx4 v[222:223], off
	v_lshl_add_u64 v[222:223], v[230:231], 0, s[58:59]
	s_mov_b32 m0, s47
	s_nop 0
	global_load_lds_dwordx4 v[222:223], off
	v_lshl_add_u64 v[222:223], v[238:239], 0, s[58:59]
	s_mov_b32 m0, s48
	s_nop 0
	global_load_lds_dwordx4 v[222:223], off
	s_waitcnt vmcnt(8)
	s_waitcnt lgkmcnt(0)
	s_barrier
	s_setprio 1
	s_waitcnt lgkmcnt(0)
	v_mfma_f32_16x16x32_bf16 v[60:63], v[144:147], v[176:179], v[60:63]
	v_mfma_f32_16x16x32_bf16 v[56:59], v[152:155], v[176:179], v[56:59]
	v_mfma_f32_16x16x32_bf16 v[44:47], v[144:147], v[184:187], v[44:47]
	v_mfma_f32_16x16x32_bf16 v[40:43], v[152:155], v[184:187], v[40:43]
	v_mfma_f32_16x16x32_bf16 v[28:31], v[144:147], v[206:209], v[28:31]
	v_mfma_f32_16x16x32_bf16 v[24:27], v[152:155], v[206:209], v[24:27]
	v_mfma_f32_16x16x32_bf16 v[12:15], v[144:147], v[214:217], v[12:15]
	v_mfma_f32_16x16x32_bf16 v[8:11], v[152:155], v[214:217], v[8:11]
	v_mfma_f32_16x16x32_bf16 v[60:63], v[148:151], v[180:183], v[60:63]
	v_mfma_f32_16x16x32_bf16 v[56:59], v[156:159], v[180:183], v[56:59]
	v_mfma_f32_16x16x32_bf16 v[44:47], v[148:151], v[188:191], v[44:47]
	v_mfma_f32_16x16x32_bf16 v[40:43], v[156:159], v[188:191], v[40:43]
	v_mfma_f32_16x16x32_bf16 v[28:31], v[148:151], v[210:213], v[28:31]
	v_mfma_f32_16x16x32_bf16 v[24:27], v[156:159], v[210:213], v[24:27]
	v_mfma_f32_16x16x32_bf16 v[12:15], v[148:151], v[218:221], v[12:15]
	v_mfma_f32_16x16x32_bf16 v[8:11], v[156:159], v[218:221], v[8:11]
	v_mfma_f32_16x16x32_bf16 v[52:55], v[160:163], v[176:179], v[52:55]
	v_mfma_f32_16x16x32_bf16 v[48:51], v[168:171], v[176:179], v[48:51]
	v_mfma_f32_16x16x32_bf16 v[36:39], v[160:163], v[184:187], v[36:39]
	v_mfma_f32_16x16x32_bf16 v[32:35], v[168:171], v[184:187], v[32:35]
	v_mfma_f32_16x16x32_bf16 v[20:23], v[160:163], v[206:209], v[20:23]
	v_mfma_f32_16x16x32_bf16 v[16:19], v[168:171], v[206:209], v[16:19]
	v_mfma_f32_16x16x32_bf16 v[4:7], v[160:163], v[214:217], v[4:7]
	v_mfma_f32_16x16x32_bf16 v[0:3], v[168:171], v[214:217], v[0:3]
	v_mfma_f32_16x16x32_bf16 v[52:55], v[164:167], v[180:183], v[52:55]
	v_mfma_f32_16x16x32_bf16 v[48:51], v[172:175], v[180:183], v[48:51]
	v_mfma_f32_16x16x32_bf16 v[36:39], v[164:167], v[188:191], v[36:39]
	v_mfma_f32_16x16x32_bf16 v[32:35], v[172:175], v[188:191], v[32:35]
	v_mfma_f32_16x16x32_bf16 v[20:23], v[164:167], v[210:213], v[20:23]
	v_mfma_f32_16x16x32_bf16 v[16:19], v[172:175], v[210:213], v[16:19]
	v_mfma_f32_16x16x32_bf16 v[4:7], v[164:167], v[218:221], v[4:7]
	v_mfma_f32_16x16x32_bf16 v[0:3], v[172:175], v[218:221], v[0:3]
	s_setprio 0
	s_barrier
	s_add_u32 s22, s22, 0x100
	s_addc_u32 s23, s23, 0
	s_add_u32 s21, s21, 0x100
	s_addc_u32 s40, s40, 0
	s_cmp_ge_i32 s41, s44
	s_mov_b32 s24, s41
	s_cbranch_scc0 .LBB0_759

; #define PG8_STAGE(bufoff, gbase, voff) do { _Pragma("unroll") for (int _i = 0; _i < 2; ++_i) \
;         __builtin_amdgcn_global_load_lds((const unsigned*)((const char*)(gbase) + (voff)[_i]), (PG8_LAS unsigned*)(lds + (bufoff) + ldsw + _i * 8192), 16, 0, 0); } while (0)
; #define PG8_LDA(dst, b, h) do { _Pragma("unroll") for (int m = 0; m < 4; ++m) _Pragma("unroll") for (int k = 0; k < 2; ++k) dst[m][k] = *(const PG8_LAS bf16x8*)(lds + PG8_SA(b, h) + aoff + m * 2048 + k * 1024); } while (0)
; #define PG8_LDB(dst, b, h) do { _Pragma("unroll") for (int n = 0; n < 2; ++n) _Pragma("unroll") for (int k = 0; k < 2; ++k) dst[n][k] = *(const PG8_LAS bf16x8*)(lds + PG8_SB(b, h) + boff + n * 2048 + k * 1024); } while (0)
; #define PG8_WAIT_V(n) asm volatile("s_waitcnt vmcnt(" #n ")" ::: "memory")
; #define PG8_WAIT_L(n) asm volatile("s_waitcnt lgkmcnt(" #n ")" ::: "memory")
; #define PG8_BAR __builtin_amdgcn_s_barrier()
; #define PG8_SCHED __builtin_amdgcn_sched_barrier(0)
;     ...
;             PG8_LDB(B0, 0, 0); PG8_LDB(B1, 0, 1); PG8_SCHED; PG8_LDA(At, 0, 0); PG8_STAGE(PG8_SA(1, 1), a1 + hstepA, voffA);
;             PG8_WAIT_V(8); PG8_WAIT_L(0); PG8_BAR; PG8_MMA(0, 0, At, B0); PG8_MMA(0, 1, At, B1); PG8_BAR; PG8_SCHED;
;             PG8_LDA(At, 0, 1); PG8_STAGE(PG8_SB(0, 0), b2, voffB); PG8_STAGE(PG8_SB(0, 1), b2 + hstepB, voffB); PG8_STAGE(PG8_SA(0, 0), a2, voffA);
;             PG8_WAIT_V(8); PG8_WAIT_L(0); PG8_BAR; PG8_MMA(1, 0, At, B0); PG8_MMA(1, 1, At, B1); PG8_BAR; PG8_SCHED;
.LBB0_779:
	s_add_u32 s21, s28, s30
	s_addc_u32 s26, s29, s31
	s_add_u32 s21, s21, 0x100
	s_addc_u32 s26, s26, 0
	s_add_u32 s27, s10, s30
	s_addc_u32 s33, s11, s31
	s_add_i32 s61, 0, 0x10000
	s_cmpk_eq_i32 s30, 0xf00
	s_cselect_b32 s41, s19, s26
	s_cselect_b32 s40, s56, s21
	v_add_u32_e32 v64, s61, v238
	s_cselect_b32 s35, s58, s33
	s_cselect_b32 s34, s59, s27
	s_add_i32 s21, 0, 0x14000
	ds_read_b128 v[132:135], v64
	ds_read_b128 v[136:139], v64 offset:1024
	ds_read_b128 v[140:143], v64 offset:2048
	ds_read_b128 v[144:147], v64 offset:3072
	v_add_u32_e32 v64, s21, v238
	ds_read_b128 v[148:151], v64
	ds_read_b128 v[156:159], v64 offset:1024
	ds_read_b128 v[160:163], v64 offset:2048
	ds_read_b128 v[164:167], v64 offset:3072
	v_lshl_add_u64 v[66:67], v[152:153], 0, s[30:31]
	s_add_i32 m0, s47, 0xc000
	ds_read_b128 v[168:171], v239
	ds_read_b128 v[172:175], v239 offset:1024
	ds_read_b128 v[176:179], v239 offset:2048
	ds_read_b128 v[180:183], v239 offset:3072
	ds_read_b128 v[184:187], v239 offset:4096
	ds_read_b128 v[188:191], v239 offset:5120
	ds_read_b128 v[218:221], v239 offset:6144
	ds_read_b128 v[222:225], v239 offset:7168
	global_load_lds_dwordx4 v[66:67], off
	v_lshl_add_u64 v[66:67], v[154:155], 0, s[30:31]
	s_add_i32 m0, s47, 0xe000
	s_nop 0
	global_load_lds_dwordx4 v[66:67], off
	s_waitcnt vmcnt(8)
	s_waitcnt lgkmcnt(0)
	s_barrier
	s_setprio 1
	s_waitcnt lgkmcnt(0)
	v_mfma_f32_16x16x32_bf16 v[128:131], v[132:135], v[168:171], v[128:131]
	v_mfma_f32_16x16x32_bf16 v[124:127], v[140:143], v[168:171], v[124:127]
	v_mfma_f32_16x16x32_bf16 v[112:115], v[132:135], v[176:179], v[112:115]
	v_mfma_f32_16x16x32_bf16 v[108:111], v[140:143], v[176:179], v[108:111]
	v_mfma_f32_16x16x32_bf16 v[96:99], v[132:135], v[184:187], v[96:99]
	v_mfma_f32_16x16x32_bf16 v[92:95], v[140:143], v[184:187], v[92:95]
	v_mfma_f32_16x16x32_bf16 v[80:83], v[132:135], v[218:221], v[80:83]
	v_mfma_f32_16x16x32_bf16 v[76:79], v[140:143], v[218:221], v[76:79]
	v_mfma_f32_16x16x32_bf16 v[128:131], v[136:139], v[172:175], v[128:131]
	v_mfma_f32_16x16x32_bf16 v[124:127], v[144:147], v[172:175], v[124:127]
	v_mfma_f32_16x16x32_bf16 v[112:115], v[136:139], v[180:183], v[112:115]
	v_mfma_f32_16x16x32_bf16 v[108:111], v[144:147], v[180:183], v[108:111]
	v_mfma_f32_16x16x32_bf16 v[96:99], v[136:139], v[188:191], v[96:99]
	v_mfma_f32_16x16x32_bf16 v[92:95], v[144:147], v[188:191], v[92:95]
	v_mfma_f32_16x16x32_bf16 v[80:83], v[136:139], v[222:225], v[80:83]
	v_mfma_f32_16x16x32_bf16 v[76:79], v[144:147], v[222:225], v[76:79]
	v_mfma_f32_16x16x32_bf16 v[120:123], v[148:151], v[168:171], v[120:123]
	v_mfma_f32_16x16x32_bf16 v[116:119], v[160:163], v[168:171], v[116:119]
	v_mfma_f32_16x16x32_bf16 v[104:107], v[148:151], v[176:179], v[104:107]
	v_mfma_f32_16x16x32_bf16 v[100:103], v[160:163], v[176:179], v[100:103]
	v_mfma_f32_16x16x32_bf16 v[88:91], v[148:151], v[184:187], v[88:91]
	v_mfma_f32_16x16x32_bf16 v[84:87], v[160:163], v[184:187], v[84:87]
	v_mfma_f32_16x16x32_bf16 v[72:75], v[148:151], v[218:221], v[72:75]
	v_mfma_f32_16x16x32_bf16 v[66:69], v[160:163], v[218:221], v[68:71]
	v_mfma_f32_16x16x32_bf16 v[120:123], v[156:159], v[172:175], v[120:123]
	v_mfma_f32_16x16x32_bf16 v[116:119], v[164:167], v[172:175], v[116:119]
	v_mfma_f32_16x16x32_bf16 v[104:107], v[156:159], v[180:183], v[104:107]
	v_mfma_f32_16x16x32_bf16 v[100:103], v[164:167], v[180:183], v[100:103]
	v_mfma_f32_16x16x32_bf16 v[88:91], v[156:159], v[188:191], v[88:91]
	v_mfma_f32_16x16x32_bf16 v[84:87], v[164:167], v[188:191], v[84:87]
	v_mfma_f32_16x16x32_bf16 v[72:75], v[156:159], v[222:225], v[72:75]
	v_mfma_f32_16x16x32_bf16 v[66:69], v[164:167], v[222:225], v[66:69]
	s_setprio 0
	s_barrier
	s_add_i32 s26, s61, s46
	v_lshl_add_u64 v[226:227], s[34:35], 0, v[210:211]
	s_mov_b32 m0, s26
	ds_read_b128 v[168:171], v239 offset:16384
	ds_read_b128 v[172:175], v239 offset:17408
	ds_read_b128 v[176:179], v239 offset:18432
	ds_read_b128 v[180:183], v239 offset:19456
	ds_read_b128 v[184:187], v239 offset:20480
	ds_read_b128 v[188:191], v239 offset:21504
	ds_read_b128 v[218:221], v239 offset:22528
	ds_read_b128 v[222:225], v239 offset:23552
	global_load_lds_dwordx4 v[226:227], off
	s_add_i32 m0, s26, 0x2000
	s_add_u32 s26, s34, 0x80000
	v_lshl_add_u64 v[228:229], s[34:35], 0, v[206:207]
	s_addc_u32 s27, s35, 0
	s_add_i32 s21, s21, s46
	global_load_lds_dwordx4 v[228:229], off
	v_lshl_add_u64 v[70:71], s[26:27], 0, v[210:211]
	s_mov_b32 m0, s21
	v_lshl_add_u64 v[230:231], s[40:41], 0, v[212:213]
	global_load_lds_dwordx4 v[70:71], off
	v_lshl_add_u64 v[70:71], s[26:27], 0, v[206:207]
	s_add_i32 m0, s21, 0x2000
	v_lshl_add_u64 v[242:243], s[40:41], 0, v[208:209]
	global_load_lds_dwordx4 v[70:71], off
	s_mov_b32 m0, s47
	s_nop 0
	global_load_lds_dwordx4 v[230:231], off
	s_mov_b32 m0, s48
	s_nop 0
	global_load_lds_dwordx4 v[242:243], off
	s_waitcnt vmcnt(8)
	s_waitcnt lgkmcnt(0)
	s_barrier
; #define PG8_STAGE(bufoff, gbase, voff) do { _Pragma("unroll") for (int _i = 0; _i < 2; ++_i) \
;         __builtin_amdgcn_global_load_lds((const unsigned*)((const char*)(gbase) + (voff)[_i]), (PG8_LAS unsigned*)(lds + (bufoff) + ldsw + _i * 8192), 16, 0, 0); } while (0)
; #define PG8_LDA(dst, b, h) do { _Pragma("unroll") for (int m = 0; m < 4; ++m) _Pragma("unroll") for (int k = 0; k < 2; ++k) dst[m][k] = *(const PG8_LAS bf16x8*)(lds + PG8_SA(b, h) + aoff + m * 2048 + k * 1024); } while (0)
; #define PG8_LDB(dst, b, h) do { _Pragma("unroll") for (int n = 0; n < 2; ++n) _Pragma("unroll") for (int k = 0; k < 2; ++k) dst[n][k] = *(const PG8_LAS bf16x8*)(lds + PG8_SB(b, h) + boff + n * 2048 + k * 1024); } while (0)
; #define PG8_WAIT_V(n) asm volatile("s_waitcnt vmcnt(" #n ")" ::: "memory")
; #define PG8_WAIT_L(n) asm volatile("s_waitcnt lgkmcnt(" #n ")" ::: "memory")
; #define PG8_BAR __builtin_amdgcn_s_barrier()
; #define PG8_SCHED __builtin_amdgcn_sched_barrier(0)
;     ...
;             PG8_WAIT_V(8); PG8_WAIT_L(0); PG8_BAR; PG8_MMA(1, 0, At, B0); PG8_MMA(1, 1, At, B1); PG8_BAR; PG8_SCHED;
;             PG8_LDB(B0, 1, 0); PG8_LDB(B1, 1, 1); PG8_SCHED; PG8_LDA(At, 1, 0); PG8_STAGE(PG8_SA(0, 1), a2 + hstepA, voffA);
;             PG8_WAIT_V(8); PG8_WAIT_L(0); PG8_BAR; PG8_MMA(0, 0, At, B0); PG8_MMA(0, 1, At, B1); PG8_BAR; PG8_SCHED;
	s_setprio 1
	s_waitcnt lgkmcnt(0)
	v_mfma_f32_16x16x32_bf16 v[60:63], v[132:135], v[168:171], v[60:63]
	v_mfma_f32_16x16x32_bf16 v[56:59], v[140:143], v[168:171], v[56:59]
	v_mfma_f32_16x16x32_bf16 v[44:47], v[132:135], v[176:179], v[44:47]
	v_mfma_f32_16x16x32_bf16 v[40:43], v[140:143], v[176:179], v[40:43]
	v_mfma_f32_16x16x32_bf16 v[28:31], v[132:135], v[184:187], v[28:31]
	v_mfma_f32_16x16x32_bf16 v[24:27], v[140:143], v[184:187], v[24:27]
	v_mfma_f32_16x16x32_bf16 v[12:15], v[132:135], v[218:221], v[12:15]
	v_mfma_f32_16x16x32_bf16 v[8:11], v[140:143], v[218:221], v[8:11]
	v_mfma_f32_16x16x32_bf16 v[60:63], v[136:139], v[172:175], v[60:63]
	v_mfma_f32_16x16x32_bf16 v[56:59], v[144:147], v[172:175], v[56:59]
	v_mfma_f32_16x16x32_bf16 v[44:47], v[136:139], v[180:183], v[44:47]
	v_mfma_f32_16x16x32_bf16 v[40:43], v[144:147], v[180:183], v[40:43]
	v_mfma_f32_16x16x32_bf16 v[28:31], v[136:139], v[188:191], v[28:31]
	v_mfma_f32_16x16x32_bf16 v[24:27], v[144:147], v[188:191], v[24:27]
	v_mfma_f32_16x16x32_bf16 v[12:15], v[136:139], v[222:225], v[12:15]
	v_mfma_f32_16x16x32_bf16 v[8:11], v[144:147], v[222:225], v[8:11]
	v_mfma_f32_16x16x32_bf16 v[52:55], v[148:151], v[168:171], v[52:55]
	v_mfma_f32_16x16x32_bf16 v[48:51], v[160:163], v[168:171], v[48:51]
	v_mfma_f32_16x16x32_bf16 v[36:39], v[148:151], v[176:179], v[36:39]
	v_mfma_f32_16x16x32_bf16 v[32:35], v[160:163], v[176:179], v[32:35]
	v_mfma_f32_16x16x32_bf16 v[20:23], v[148:151], v[184:187], v[20:23]
	v_mfma_f32_16x16x32_bf16 v[16:19], v[160:163], v[184:187], v[16:19]
	v_mfma_f32_16x16x32_bf16 v[4:7], v[148:151], v[218:221], v[4:7]
	v_mfma_f32_16x16x32_bf16 v[0:3], v[160:163], v[218:221], v[0:3]
	v_mfma_f32_16x16x32_bf16 v[52:55], v[156:159], v[172:175], v[52:55]
	v_mfma_f32_16x16x32_bf16 v[48:51], v[164:167], v[172:175], v[48:51]
	v_mfma_f32_16x16x32_bf16 v[36:39], v[156:159], v[180:183], v[36:39]
	v_mfma_f32_16x16x32_bf16 v[32:35], v[164:167], v[180:183], v[32:35]
	v_mfma_f32_16x16x32_bf16 v[20:23], v[156:159], v[188:191], v[20:23]
	v_mfma_f32_16x16x32_bf16 v[16:19], v[164:167], v[188:191], v[16:19]
	v_mfma_f32_16x16x32_bf16 v[4:7], v[156:159], v[222:225], v[4:7]
	v_mfma_f32_16x16x32_bf16 v[0:3], v[164:167], v[222:225], v[0:3]
	s_setprio 0
	s_barrier
	s_add_i32 s21, 0, 0x18000
	v_add_u32_e32 v64, s21, v238
	s_add_i32 s33, 0, 0x1c000
	ds_read_b128 v[132:135], v64
	ds_read_b128 v[136:139], v64 offset:1024
	ds_read_b128 v[140:143], v64 offset:2048
	ds_read_b128 v[144:147], v64 offset:3072
	v_add_u32_e32 v64, s33, v238
	ds_read_b128 v[148:151], v64
	ds_read_b128 v[156:159], v64 offset:1024
	ds_read_b128 v[160:163], v64 offset:2048
	ds_read_b128 v[164:167], v64 offset:3072
	s_add_u32 s26, s40, 0x80000
	s_addc_u32 s27, s41, 0
	s_mov_b32 m0, s49
	v_lshl_add_u64 v[70:71], s[26:27], 0, v[212:213]
	ds_read_b128 v[168:171], v239 offset:32768
	ds_read_b128 v[172:175], v239 offset:33792
	ds_read_b128 v[176:179], v239 offset:34816
	ds_read_b128 v[180:183], v239 offset:35840
	ds_read_b128 v[184:187], v239 offset:36864
	ds_read_b128 v[188:191], v239 offset:37888
	ds_read_b128 v[218:221], v239 offset:38912
	ds_read_b128 v[222:225], v239 offset:39936
	global_load_lds_dwordx4 v[70:71], off
	v_lshl_add_u64 v[70:71], s[26:27], 0, v[208:209]
	s_mov_b32 m0, s50
	s_nop 0
	global_load_lds_dwordx4 v[70:71], off
	s_waitcnt vmcnt(8)
	s_waitcnt lgkmcnt(0)
	s_barrier
	s_setprio 1
	s_waitcnt lgkmcnt(0)
	v_mfma_f32_16x16x32_bf16 v[128:131], v[132:135], v[168:171], v[128:131]
	v_mfma_f32_16x16x32_bf16 v[124:127], v[140:143], v[168:171], v[124:127]
	v_mfma_f32_16x16x32_bf16 v[112:115], v[132:135], v[176:179], v[112:115]
	v_mfma_f32_16x16x32_bf16 v[108:111], v[140:143], v[176:179], v[108:111]
	v_mfma_f32_16x16x32_bf16 v[96:99], v[132:135], v[184:187], v[96:99]
	v_mfma_f32_16x16x32_bf16 v[92:95], v[140:143], v[184:187], v[92:95]
	v_mfma_f32_16x16x32_bf16 v[80:83], v[132:135], v[218:221], v[80:83]
	v_mfma_f32_16x16x32_bf16 v[76:79], v[140:143], v[218:221], v[76:79]
	v_mfma_f32_16x16x32_bf16 v[128:131], v[136:139], v[172:175], v[128:131]
	v_mfma_f32_16x16x32_bf16 v[124:127], v[144:147], v[172:175], v[124:127]
	v_mfma_f32_16x16x32_bf16 v[112:115], v[136:139], v[180:183], v[112:115]
	v_mfma_f32_16x16x32_bf16 v[108:111], v[144:147], v[180:183], v[108:111]
	v_mfma_f32_16x16x32_bf16 v[96:99], v[136:139], v[188:191], v[96:99]
	v_mfma_f32_16x16x32_bf16 v[92:95], v[144:147], v[188:191], v[92:95]
	v_mfma_f32_16x16x32_bf16 v[80:83], v[136:139], v[222:225], v[80:83]
	v_mfma_f32_16x16x32_bf16 v[76:79], v[144:147], v[222:225], v[76:79]
	v_mfma_f32_16x16x32_bf16 v[120:123], v[148:151], v[168:171], v[120:123]
	v_mfma_f32_16x16x32_bf16 v[116:119], v[160:163], v[168:171], v[116:119]
	v_mfma_f32_16x16x32_bf16 v[104:107], v[148:151], v[176:179], v[104:107]
	v_mfma_f32_16x16x32_bf16 v[100:103], v[160:163], v[176:179], v[100:103]
	v_mfma_f32_16x16x32_bf16 v[88:91], v[148:151], v[184:187], v[88:91]
	v_mfma_f32_16x16x32_bf16 v[84:87], v[160:163], v[184:187], v[84:87]
	v_mfma_f32_16x16x32_bf16 v[70:73], v[148:151], v[218:221], v[72:75]
	v_mfma_f32_16x16x32_bf16 v[66:69], v[160:163], v[218:221], v[66:69]
	v_mfma_f32_16x16x32_bf16 v[120:123], v[156:159], v[172:175], v[120:123]
	v_mfma_f32_16x16x32_bf16 v[116:119], v[164:167], v[172:175], v[116:119]
	v_mfma_f32_16x16x32_bf16 v[104:107], v[156:159], v[180:183], v[104:107]
	v_mfma_f32_16x16x32_bf16 v[100:103], v[164:167], v[180:183], v[100:103]
	v_mfma_f32_16x16x32_bf16 v[88:91], v[156:159], v[188:191], v[88:91]
	v_mfma_f32_16x16x32_bf16 v[84:87], v[164:167], v[188:191], v[84:87]
	v_mfma_f32_16x16x32_bf16 v[72:75], v[156:159], v[222:225], v[70:73]
	v_mfma_f32_16x16x32_bf16 v[68:71], v[164:167], v[222:225], v[66:69]
	s_setprio 0
	s_barrier
; #define PG8_STAGE(bufoff, gbase, voff) do { _Pragma("unroll") for (int _i = 0; _i < 2; ++_i) \
;         __builtin_amdgcn_global_load_lds((const unsigned*)((const char*)(gbase) + (voff)[_i]), (PG8_LAS unsigned*)(lds + (bufoff) + ldsw + _i * 8192), 16, 0, 0); } while (0)
; #define PG8_LDA(dst, b, h) do { _Pragma("unroll") for (int m = 0; m < 4; ++m) _Pragma("unroll") for (int k = 0; k < 2; ++k) dst[m][k] = *(const PG8_LAS bf16x8*)(lds + PG8_SA(b, h) + aoff + m * 2048 + k * 1024); } while (0)
; #define PG8_WAIT_V(n) asm volatile("s_waitcnt vmcnt(" #n ")" ::: "memory")
; #define PG8_WAIT_L(n) asm volatile("s_waitcnt lgkmcnt(" #n ")" ::: "memory")
; #define PG8_BAR __builtin_amdgcn_s_barrier()
; #define PG8_SCHED __builtin_amdgcn_sched_barrier(0)
;     ...
;             PG8_LDA(At, 1, 1); PG8_STAGE(PG8_SB(1, 0), b3, voffB); PG8_STAGE(PG8_SB(1, 1), b3 + hstepB, voffB); PG8_STAGE(PG8_SA(1, 0), a3, voffA);
;             PG8_WAIT_V(8); PG8_WAIT_L(0); PG8_BAR; PG8_MMA(1, 0, At, B0); PG8_MMA(1, 1, At, B1); PG8_BAR; PG8_SCHED;
	s_mov_b64 s[40:41], 0x80
	s_add_i32 s21, s21, s46
	v_lshl_add_u64 v[66:67], v[226:227], 0, s[40:41]
	s_mov_b32 m0, s21
	ds_read_b128 v[168:171], v239 offset:49152
	ds_read_b128 v[172:175], v239 offset:50176
	ds_read_b128 v[176:179], v239 offset:51200
	ds_read_b128 v[180:183], v239 offset:52224
	ds_read_b128 v[184:187], v239 offset:53248
	ds_read_b128 v[188:191], v239 offset:54272
	ds_read_b128 v[218:221], v239 offset:55296
	ds_read_b128 v[222:225], v239 offset:56320
	global_load_lds_dwordx4 v[66:67], off
	s_add_i32 m0, s21, 0x2000
	s_add_u32 s26, s34, 0x80080
	v_lshl_add_u64 v[66:67], v[228:229], 0, s[40:41]
	s_addc_u32 s27, s35, 0
	s_add_i32 s21, s33, s46
	global_load_lds_dwordx4 v[66:67], off
	v_lshl_add_u64 v[66:67], s[26:27], 0, v[210:211]
	s_mov_b32 m0, s21
	s_nop 0
	global_load_lds_dwordx4 v[66:67], off
	v_lshl_add_u64 v[66:67], s[26:27], 0, v[206:207]
	s_add_i32 m0, s21, 0x2000
	s_nop 0
	global_load_lds_dwordx4 v[66:67], off
	v_lshl_add_u64 v[66:67], v[230:231], 0, s[40:41]
	s_mov_b32 m0, s53
	s_nop 0
	global_load_lds_dwordx4 v[66:67], off
	v_lshl_add_u64 v[66:67], v[242:243], 0, s[40:41]
	s_mov_b32 m0, s54
	s_nop 0
	global_load_lds_dwordx4 v[66:67], off
	s_waitcnt vmcnt(8)
	s_waitcnt lgkmcnt(0)
	s_barrier
	s_setprio 1
	s_waitcnt lgkmcnt(0)
	v_mfma_f32_16x16x32_bf16 v[60:63], v[132:135], v[168:171], v[60:63]
	v_mfma_f32_16x16x32_bf16 v[56:59], v[140:143], v[168:171], v[56:59]
	v_mfma_f32_16x16x32_bf16 v[44:47], v[132:135], v[176:179], v[44:47]
	v_mfma_f32_16x16x32_bf16 v[40:43], v[140:143], v[176:179], v[40:43]
	v_mfma_f32_16x16x32_bf16 v[28:31], v[132:135], v[184:187], v[28:31]
	v_mfma_f32_16x16x32_bf16 v[24:27], v[140:143], v[184:187], v[24:27]
	v_mfma_f32_16x16x32_bf16 v[12:15], v[132:135], v[218:221], v[12:15]
	v_mfma_f32_16x16x32_bf16 v[8:11], v[140:143], v[218:221], v[8:11]
	v_mfma_f32_16x16x32_bf16 v[60:63], v[136:139], v[172:175], v[60:63]
	v_mfma_f32_16x16x32_bf16 v[56:59], v[144:147], v[172:175], v[56:59]
	v_mfma_f32_16x16x32_bf16 v[44:47], v[136:139], v[180:183], v[44:47]
	v_mfma_f32_16x16x32_bf16 v[40:43], v[144:147], v[180:183], v[40:43]
	v_mfma_f32_16x16x32_bf16 v[28:31], v[136:139], v[188:191], v[28:31]
	v_mfma_f32_16x16x32_bf16 v[24:27], v[144:147], v[188:191], v[24:27]
	v_mfma_f32_16x16x32_bf16 v[12:15], v[136:139], v[222:225], v[12:15]
	v_mfma_f32_16x16x32_bf16 v[8:11], v[144:147], v[222:225], v[8:11]
	v_mfma_f32_16x16x32_bf16 v[52:55], v[148:151], v[168:171], v[52:55]
	v_mfma_f32_16x16x32_bf16 v[48:51], v[160:163], v[168:171], v[48:51]
	v_mfma_f32_16x16x32_bf16 v[36:39], v[148:151], v[176:179], v[36:39]
	v_mfma_f32_16x16x32_bf16 v[32:35], v[160:163], v[176:179], v[32:35]
	v_mfma_f32_16x16x32_bf16 v[20:23], v[148:151], v[184:187], v[20:23]
	v_mfma_f32_16x16x32_bf16 v[16:19], v[160:163], v[184:187], v[16:19]
	v_mfma_f32_16x16x32_bf16 v[4:7], v[148:151], v[218:221], v[4:7]
	v_mfma_f32_16x16x32_bf16 v[0:3], v[160:163], v[218:221], v[0:3]
	v_mfma_f32_16x16x32_bf16 v[52:55], v[156:159], v[172:175], v[52:55]
	v_mfma_f32_16x16x32_bf16 v[48:51], v[164:167], v[172:175], v[48:51]
	v_mfma_f32_16x16x32_bf16 v[36:39], v[156:159], v[180:183], v[36:39]
	v_mfma_f32_16x16x32_bf16 v[32:35], v[164:167], v[180:183], v[32:35]
	v_mfma_f32_16x16x32_bf16 v[20:23], v[156:159], v[188:191], v[20:23]
	v_mfma_f32_16x16x32_bf16 v[16:19], v[164:167], v[188:191], v[16:19]
	v_mfma_f32_16x16x32_bf16 v[4:7], v[156:159], v[222:225], v[4:7]
	v_mfma_f32_16x16x32_bf16 v[0:3], v[164:167], v[222:225], v[0:3]
	s_setprio 0
	s_barrier
	s_add_i32 s60, s60, 2
	s_add_u32 s30, s30, 0x100
	s_addc_u32 s31, s31, 0
	s_cmp_gt_u32 s60, 29
	s_cbranch_scc1 .LBB0_782

; #define PG8_STAGE(bufoff, gbase, voff) do { _Pragma("unroll") for (int _i = 0; _i < 2; ++_i) \
;         __builtin_amdgcn_global_load_lds((const unsigned*)((const char*)(gbase) + (voff)[_i]), (PG8_LAS unsigned*)(lds + (bufoff) + ldsw + _i * 8192), 16, 0, 0); } while (0)
; #define PG8_LDA(dst, b, h) do { _Pragma("unroll") for (int m = 0; m < 4; ++m) _Pragma("unroll") for (int k = 0; k < 2; ++k) dst[m][k] = *(const PG8_LAS bf16x8*)(lds + PG8_SA(b, h) + aoff + m * 2048 + k * 1024); } while (0)
; #define PG8_LDB(dst, b, h) do { _Pragma("unroll") for (int n = 0; n < 2; ++n) _Pragma("unroll") for (int k = 0; k < 2; ++k) dst[n][k] = *(const PG8_LAS bf16x8*)(lds + PG8_SB(b, h) + boff + n * 2048 + k * 1024); } while (0)
; #define PG8_WAIT_V(n) asm volatile("s_waitcnt vmcnt(" #n ")" ::: "memory")
; #define PG8_WAIT_L(n) asm volatile("s_waitcnt lgkmcnt(" #n ")" ::: "memory")
; #define PG8_BAR __builtin_amdgcn_s_barrier()
; #define PG8_SCHED __builtin_amdgcn_sched_barrier(0)
;     ...
;             const bool last = (t == nt - 2);
;             const char* a1 = cA + (size_t)(t + 1) * kstep;
;             const char* a2 = last ? nA : cA + (size_t)(t + 2) * kstep; const char* b2 = last ? nB : cB + (size_t)(t + 2) * kstep;
;             const char* a3 = a2 + kstep; const char* b3 = b2 + kstep;
;             if (last && has_next) S.a_ready(nxt);
;             if constexpr (SP2) {
;             PG8_LDB(B0, 0, 0); PG8_LDB(B1, 0, 1); PG8_SCHED; PG8_LDA(At, 0, 0); PG8_STAGE(PG8_SA(1, 1), a1 + hstepA, voffA);
;             PG8_WAIT_V(8); PG8_WAIT_L(0); PG8_BAR; PG8_MMA(0, 0, At, B0); PG8_MMA(0, 1, At, B1); PG8_BAR; PG8_SCHED;
;             PG8_LDA(At, 0, 1); PG8_STAGE(PG8_SB(0, 0), b2, voffB); PG8_STAGE(PG8_SB(0, 1), b2 + hstepB, voffB); PG8_STAGE(PG8_SA(0, 0), a2, voffA);
;             PG8_WAIT_V(8); PG8_WAIT_L(0); PG8_BAR; PG8_MMA(1, 0, At, B0); PG8_MMA(1, 1, At, B1); PG8_BAR; PG8_SCHED;
.LBB0_849:
	s_add_u32 s28, s24, 0xfffc0080
	s_addc_u32 s29, s25, -1
	s_add_i32 s53, 0, 0x10000
	s_cmp_eq_u32 s52, 12
	s_cselect_b32 s31, s15, s29
	s_cselect_b32 s30, s21, s28
	s_cselect_b32 s29, s13, s33
	s_cselect_b32 s28, s26, s27
	s_add_i32 s56, 0, 0x14000
	v_add_u32_e32 v142, s53, v174
	v_add_u32_e32 v168, s56, v174
	ds_read_b128 v[130:133], v142
	ds_read_b128 v[134:137], v142 offset:1024
	ds_read_b128 v[138:141], v142 offset:2048
	ds_read_b128 v[142:145], v142 offset:3072
	ds_read_b128 v[146:149], v168
	ds_read_b128 v[160:163], v168 offset:1024
	ds_read_b128 v[164:167], v168 offset:2048
	ds_read_b128 v[168:171], v168 offset:3072
	v_lshl_add_u64 v[222:223], s[24:25], 0, v[156:157]
	s_add_i32 m0, s41, 0xc000
	ds_read_b128 v[176:179], v175
	ds_read_b128 v[180:183], v175 offset:1024
	ds_read_b128 v[184:187], v175 offset:2048
	ds_read_b128 v[188:191], v175 offset:3072
	ds_read_b128 v[206:209], v175 offset:4096
	ds_read_b128 v[210:213], v175 offset:5120
	ds_read_b128 v[214:217], v175 offset:6144
	ds_read_b128 v[218:221], v175 offset:7168
	global_load_lds_dwordx4 v[222:223], off
	v_lshl_add_u64 v[222:223], s[24:25], 0, v[158:159]
	s_add_i32 m0, s41, 0xe000
	s_nop 0
	global_load_lds_dwordx4 v[222:223], off
	s_waitcnt vmcnt(8)
	s_waitcnt lgkmcnt(0)
	s_barrier
	s_setprio 1
	s_waitcnt lgkmcnt(0)
	v_mfma_f32_16x16x32_bf16 v[126:129], v[130:133], v[176:179], v[126:129]
	v_mfma_f32_16x16x32_bf16 v[122:125], v[138:141], v[176:179], v[122:125]
	v_mfma_f32_16x16x32_bf16 v[118:121], v[130:133], v[184:187], v[118:121]
	v_mfma_f32_16x16x32_bf16 v[114:117], v[138:141], v[184:187], v[114:117]
	v_mfma_f32_16x16x32_bf16 v[94:97], v[130:133], v[206:209], v[94:97]
	v_mfma_f32_16x16x32_bf16 v[90:93], v[138:141], v[206:209], v[90:93]
	v_mfma_f32_16x16x32_bf16 v[78:81], v[130:133], v[214:217], v[78:81]
	v_mfma_f32_16x16x32_bf16 v[74:77], v[138:141], v[214:217], v[74:77]
	v_mfma_f32_16x16x32_bf16 v[126:129], v[134:137], v[180:183], v[126:129]
	v_mfma_f32_16x16x32_bf16 v[122:125], v[142:145], v[180:183], v[122:125]
	v_mfma_f32_16x16x32_bf16 v[118:121], v[134:137], v[188:191], v[118:121]
	v_mfma_f32_16x16x32_bf16 v[114:117], v[142:145], v[188:191], v[114:117]
	v_mfma_f32_16x16x32_bf16 v[94:97], v[134:137], v[210:213], v[94:97]
	v_mfma_f32_16x16x32_bf16 v[90:93], v[142:145], v[210:213], v[90:93]
	v_mfma_f32_16x16x32_bf16 v[78:81], v[134:137], v[218:221], v[78:81]
	v_mfma_f32_16x16x32_bf16 v[74:77], v[142:145], v[218:221], v[74:77]
	v_mfma_f32_16x16x32_bf16 v[110:113], v[146:149], v[176:179], v[110:113]
	v_mfma_f32_16x16x32_bf16 v[106:109], v[164:167], v[176:179], v[106:109]
	v_mfma_f32_16x16x32_bf16 v[102:105], v[146:149], v[184:187], v[102:105]
	v_mfma_f32_16x16x32_bf16 v[98:101], v[164:167], v[184:187], v[98:101]
	v_mfma_f32_16x16x32_bf16 v[86:89], v[146:149], v[206:209], v[86:89]
	v_mfma_f32_16x16x32_bf16 v[82:85], v[164:167], v[206:209], v[82:85]
	v_mfma_f32_16x16x32_bf16 v[70:73], v[146:149], v[214:217], v[70:73]
	v_mfma_f32_16x16x32_bf16 v[66:69], v[164:167], v[214:217], v[66:69]
	v_mfma_f32_16x16x32_bf16 v[110:113], v[160:163], v[180:183], v[110:113]
	v_mfma_f32_16x16x32_bf16 v[106:109], v[168:171], v[180:183], v[106:109]
	v_mfma_f32_16x16x32_bf16 v[102:105], v[160:163], v[188:191], v[102:105]
	v_mfma_f32_16x16x32_bf16 v[98:101], v[168:171], v[188:191], v[98:101]
	v_mfma_f32_16x16x32_bf16 v[86:89], v[160:163], v[210:213], v[86:89]
	v_mfma_f32_16x16x32_bf16 v[82:85], v[168:171], v[210:213], v[82:85]
	v_mfma_f32_16x16x32_bf16 v[70:73], v[160:163], v[218:221], v[70:73]
	v_mfma_f32_16x16x32_bf16 v[66:69], v[168:171], v[218:221], v[66:69]
	s_setprio 0
	s_barrier
	s_add_i32 s53, s53, s40
	v_lshl_add_u64 v[222:223], s[28:29], 0, v[64:65]
	s_mov_b32 m0, s53
	ds_read_b128 v[176:179], v175 offset:16384
	ds_read_b128 v[180:183], v175 offset:17408
	ds_read_b128 v[184:187], v175 offset:18432
	ds_read_b128 v[188:191], v175 offset:19456
	ds_read_b128 v[206:209], v175 offset:20480
	ds_read_b128 v[210:213], v175 offset:21504
	ds_read_b128 v[214:217], v175 offset:22528
	ds_read_b128 v[218:221], v175 offset:23552
	global_load_lds_dwordx4 v[222:223], off
	s_add_i32 m0, s53, 0x2000
	s_add_u32 s54, s28, 0x40000
	v_lshl_add_u64 v[224:225], s[28:29], 0, v[150:151]
	s_addc_u32 s55, s29, 0
	s_add_i32 s53, s56, s40
	global_load_lds_dwordx4 v[224:225], off
	v_lshl_add_u64 v[226:227], s[54:55], 0, v[64:65]
	s_mov_b32 m0, s53
	v_lshl_add_u64 v[228:229], s[30:31], 0, v[152:153]
	global_load_lds_dwordx4 v[226:227], off
	v_lshl_add_u64 v[226:227], s[54:55], 0, v[150:151]
	s_add_i32 m0, s53, 0x2000
	s_nop 0
	global_load_lds_dwordx4 v[226:227], off
	v_lshl_add_u64 v[226:227], s[30:31], 0, v[154:155]
	s_mov_b32 m0, s41
	s_nop 0
	global_load_lds_dwordx4 v[226:227], off
	s_mov_b32 m0, s44
	s_nop 0
	global_load_lds_dwordx4 v[228:229], off
	s_waitcnt vmcnt(8)
	s_waitcnt lgkmcnt(0)
	s_barrier
; #define PG8_STAGE(bufoff, gbase, voff) do { _Pragma("unroll") for (int _i = 0; _i < 2; ++_i) \
;         __builtin_amdgcn_global_load_lds((const unsigned*)((const char*)(gbase) + (voff)[_i]), (PG8_LAS unsigned*)(lds + (bufoff) + ldsw + _i * 8192), 16, 0, 0); } while (0)
; #define PG8_LDA(dst, b, h) do { _Pragma("unroll") for (int m = 0; m < 4; ++m) _Pragma("unroll") for (int k = 0; k < 2; ++k) dst[m][k] = *(const PG8_LAS bf16x8*)(lds + PG8_SA(b, h) + aoff + m * 2048 + k * 1024); } while (0)
; #define PG8_LDB(dst, b, h) do { _Pragma("unroll") for (int n = 0; n < 2; ++n) _Pragma("unroll") for (int k = 0; k < 2; ++k) dst[n][k] = *(const PG8_LAS bf16x8*)(lds + PG8_SB(b, h) + boff + n * 2048 + k * 1024); } while (0)
; #define PG8_WAIT_V(n) asm volatile("s_waitcnt vmcnt(" #n ")" ::: "memory")
; #define PG8_WAIT_L(n) asm volatile("s_waitcnt lgkmcnt(" #n ")" ::: "memory")
; #define PG8_BAR __builtin_amdgcn_s_barrier()
; #define PG8_SCHED __builtin_amdgcn_sched_barrier(0)
;     ...
;             PG8_WAIT_V(8); PG8_WAIT_L(0); PG8_BAR; PG8_MMA(1, 0, At, B0); PG8_MMA(1, 1, At, B1); PG8_BAR; PG8_SCHED;
;             PG8_LDB(B0, 1, 0); PG8_LDB(B1, 1, 1); PG8_SCHED; PG8_LDA(At, 1, 0); PG8_STAGE(PG8_SA(0, 1), a2 + hstepA, voffA);
;             PG8_WAIT_V(8); PG8_WAIT_L(0); PG8_BAR; PG8_MMA(0, 0, At, B0); PG8_MMA(0, 1, At, B1); PG8_BAR; PG8_SCHED;
	s_setprio 1
	s_waitcnt lgkmcnt(0)
	v_mfma_f32_16x16x32_bf16 v[60:63], v[130:133], v[176:179], v[60:63]
	v_mfma_f32_16x16x32_bf16 v[56:59], v[138:141], v[176:179], v[56:59]
	v_mfma_f32_16x16x32_bf16 v[44:47], v[130:133], v[184:187], v[44:47]
	v_mfma_f32_16x16x32_bf16 v[40:43], v[138:141], v[184:187], v[40:43]
	v_mfma_f32_16x16x32_bf16 v[28:31], v[130:133], v[206:209], v[28:31]
	v_mfma_f32_16x16x32_bf16 v[24:27], v[138:141], v[206:209], v[24:27]
	v_mfma_f32_16x16x32_bf16 v[12:15], v[130:133], v[214:217], v[12:15]
	v_mfma_f32_16x16x32_bf16 v[8:11], v[138:141], v[214:217], v[8:11]
	v_mfma_f32_16x16x32_bf16 v[60:63], v[134:137], v[180:183], v[60:63]
	v_mfma_f32_16x16x32_bf16 v[56:59], v[142:145], v[180:183], v[56:59]
	v_mfma_f32_16x16x32_bf16 v[44:47], v[134:137], v[188:191], v[44:47]
	v_mfma_f32_16x16x32_bf16 v[40:43], v[142:145], v[188:191], v[40:43]
	v_mfma_f32_16x16x32_bf16 v[28:31], v[134:137], v[210:213], v[28:31]
	v_mfma_f32_16x16x32_bf16 v[24:27], v[142:145], v[210:213], v[24:27]
	v_mfma_f32_16x16x32_bf16 v[12:15], v[134:137], v[218:221], v[12:15]
	v_mfma_f32_16x16x32_bf16 v[8:11], v[142:145], v[218:221], v[8:11]
	v_mfma_f32_16x16x32_bf16 v[52:55], v[146:149], v[176:179], v[52:55]
	v_mfma_f32_16x16x32_bf16 v[48:51], v[164:167], v[176:179], v[48:51]
	v_mfma_f32_16x16x32_bf16 v[36:39], v[146:149], v[184:187], v[36:39]
	v_mfma_f32_16x16x32_bf16 v[32:35], v[164:167], v[184:187], v[32:35]
	v_mfma_f32_16x16x32_bf16 v[20:23], v[146:149], v[206:209], v[20:23]
	v_mfma_f32_16x16x32_bf16 v[16:19], v[164:167], v[206:209], v[16:19]
	v_mfma_f32_16x16x32_bf16 v[4:7], v[146:149], v[214:217], v[4:7]
	v_mfma_f32_16x16x32_bf16 v[0:3], v[164:167], v[214:217], v[0:3]
	v_mfma_f32_16x16x32_bf16 v[52:55], v[160:163], v[180:183], v[52:55]
	v_mfma_f32_16x16x32_bf16 v[48:51], v[168:171], v[180:183], v[48:51]
	v_mfma_f32_16x16x32_bf16 v[36:39], v[160:163], v[188:191], v[36:39]
	v_mfma_f32_16x16x32_bf16 v[32:35], v[168:171], v[188:191], v[32:35]
	v_mfma_f32_16x16x32_bf16 v[20:23], v[160:163], v[210:213], v[20:23]
	v_mfma_f32_16x16x32_bf16 v[16:19], v[168:171], v[210:213], v[16:19]
	v_mfma_f32_16x16x32_bf16 v[4:7], v[160:163], v[218:221], v[4:7]
	v_mfma_f32_16x16x32_bf16 v[0:3], v[168:171], v[218:221], v[0:3]
	s_setprio 0
	s_barrier
	s_add_i32 s53, 0, 0x18000
	s_add_i32 s54, 0, 0x1c000
	v_add_u32_e32 v142, s53, v174
	v_add_u32_e32 v168, s54, v174
	ds_read_b128 v[130:133], v142
	ds_read_b128 v[134:137], v142 offset:1024
	ds_read_b128 v[138:141], v142 offset:2048
	ds_read_b128 v[142:145], v142 offset:3072
	ds_read_b128 v[146:149], v168
	ds_read_b128 v[160:163], v168 offset:1024
	ds_read_b128 v[164:167], v168 offset:2048
	ds_read_b128 v[168:171], v168 offset:3072
	s_add_u32 s30, s30, 0x40000
	s_addc_u32 s31, s31, 0
	s_mov_b32 m0, s45
	v_lshl_add_u64 v[230:231], s[30:31], 0, v[154:155]
	ds_read_b128 v[176:179], v175 offset:32768
	ds_read_b128 v[180:183], v175 offset:33792
	ds_read_b128 v[184:187], v175 offset:34816
	ds_read_b128 v[188:191], v175 offset:35840
	ds_read_b128 v[206:209], v175 offset:36864
	ds_read_b128 v[210:213], v175 offset:37888
	ds_read_b128 v[214:217], v175 offset:38912
	ds_read_b128 v[218:221], v175 offset:39936
	global_load_lds_dwordx4 v[230:231], off
	v_lshl_add_u64 v[230:231], s[30:31], 0, v[152:153]
	s_mov_b32 m0, s46
	s_nop 0
	global_load_lds_dwordx4 v[230:231], off
	s_waitcnt vmcnt(8)
	s_waitcnt lgkmcnt(0)
	s_barrier
	s_setprio 1
	s_waitcnt lgkmcnt(0)
	v_mfma_f32_16x16x32_bf16 v[126:129], v[130:133], v[176:179], v[126:129]
	v_mfma_f32_16x16x32_bf16 v[122:125], v[138:141], v[176:179], v[122:125]
	v_mfma_f32_16x16x32_bf16 v[118:121], v[130:133], v[184:187], v[118:121]
	v_mfma_f32_16x16x32_bf16 v[114:117], v[138:141], v[184:187], v[114:117]
	v_mfma_f32_16x16x32_bf16 v[94:97], v[130:133], v[206:209], v[94:97]
	v_mfma_f32_16x16x32_bf16 v[90:93], v[138:141], v[206:209], v[90:93]
	v_mfma_f32_16x16x32_bf16 v[78:81], v[130:133], v[214:217], v[78:81]
	v_mfma_f32_16x16x32_bf16 v[74:77], v[138:141], v[214:217], v[74:77]
	v_mfma_f32_16x16x32_bf16 v[126:129], v[134:137], v[180:183], v[126:129]
	v_mfma_f32_16x16x32_bf16 v[122:125], v[142:145], v[180:183], v[122:125]
	v_mfma_f32_16x16x32_bf16 v[118:121], v[134:137], v[188:191], v[118:121]
	v_mfma_f32_16x16x32_bf16 v[114:117], v[142:145], v[188:191], v[114:117]
	v_mfma_f32_16x16x32_bf16 v[94:97], v[134:137], v[210:213], v[94:97]
	v_mfma_f32_16x16x32_bf16 v[90:93], v[142:145], v[210:213], v[90:93]
	v_mfma_f32_16x16x32_bf16 v[78:81], v[134:137], v[218:221], v[78:81]
	v_mfma_f32_16x16x32_bf16 v[74:77], v[142:145], v[218:221], v[74:77]
	v_mfma_f32_16x16x32_bf16 v[110:113], v[146:149], v[176:179], v[110:113]
	v_mfma_f32_16x16x32_bf16 v[106:109], v[164:167], v[176:179], v[106:109]
	v_mfma_f32_16x16x32_bf16 v[102:105], v[146:149], v[184:187], v[102:105]
	v_mfma_f32_16x16x32_bf16 v[98:101], v[164:167], v[184:187], v[98:101]
	v_mfma_f32_16x16x32_bf16 v[86:89], v[146:149], v[206:209], v[86:89]
	v_mfma_f32_16x16x32_bf16 v[82:85], v[164:167], v[206:209], v[82:85]
	v_mfma_f32_16x16x32_bf16 v[70:73], v[146:149], v[214:217], v[70:73]
	v_mfma_f32_16x16x32_bf16 v[66:69], v[164:167], v[214:217], v[66:69]
	v_mfma_f32_16x16x32_bf16 v[110:113], v[160:163], v[180:183], v[110:113]
	v_mfma_f32_16x16x32_bf16 v[106:109], v[168:171], v[180:183], v[106:109]
	v_mfma_f32_16x16x32_bf16 v[102:105], v[160:163], v[188:191], v[102:105]
	v_mfma_f32_16x16x32_bf16 v[98:101], v[168:171], v[188:191], v[98:101]
	v_mfma_f32_16x16x32_bf16 v[86:89], v[160:163], v[210:213], v[86:89]
	v_mfma_f32_16x16x32_bf16 v[82:85], v[168:171], v[210:213], v[82:85]
	v_mfma_f32_16x16x32_bf16 v[70:73], v[160:163], v[218:221], v[70:73]
	v_mfma_f32_16x16x32_bf16 v[66:69], v[168:171], v[218:221], v[66:69]
	s_setprio 0
	s_barrier
; #define PG8_STAGE(bufoff, gbase, voff) do { _Pragma("unroll") for (int _i = 0; _i < 2; ++_i) \
;         __builtin_amdgcn_global_load_lds((const unsigned*)((const char*)(gbase) + (voff)[_i]), (PG8_LAS unsigned*)(lds + (bufoff) + ldsw + _i * 8192), 16, 0, 0); } while (0)
; #define PG8_LDA(dst, b, h) do { _Pragma("unroll") for (int m = 0; m < 4; ++m) _Pragma("unroll") for (int k = 0; k < 2; ++k) dst[m][k] = *(const PG8_LAS bf16x8*)(lds + PG8_SA(b, h) + aoff + m * 2048 + k * 1024); } while (0)
; #define PG8_WAIT_V(n) asm volatile("s_waitcnt vmcnt(" #n ")" ::: "memory")
; #define PG8_WAIT_L(n) asm volatile("s_waitcnt lgkmcnt(" #n ")" ::: "memory")
; #define PG8_BAR __builtin_amdgcn_s_barrier()
; #define PG8_SCHED __builtin_amdgcn_sched_barrier(0)
;     ...
;             PG8_LDA(At, 1, 1); PG8_STAGE(PG8_SB(1, 0), b3, voffB); PG8_STAGE(PG8_SB(1, 1), b3 + hstepB, voffB); PG8_STAGE(PG8_SA(1, 0), a3, voffA);
;             PG8_WAIT_V(8); PG8_WAIT_L(0); PG8_BAR; PG8_MMA(1, 0, At, B0); PG8_MMA(1, 1, At, B1); PG8_BAR; PG8_SCHED;
;     ...
;         if constexpr (ALIGN_EPI) { if (wr == 0) PG8_BAR; }
	s_add_i32 s30, s53, s40
	v_lshl_add_u64 v[222:223], v[222:223], 0, s[58:59]
	s_mov_b32 m0, s30
	ds_read_b128 v[176:179], v175 offset:49152
	ds_read_b128 v[180:183], v175 offset:50176
	ds_read_b128 v[184:187], v175 offset:51200
	ds_read_b128 v[188:191], v175 offset:52224
	ds_read_b128 v[206:209], v175 offset:53248
	ds_read_b128 v[210:213], v175 offset:54272
	ds_read_b128 v[214:217], v175 offset:55296
	ds_read_b128 v[218:221], v175 offset:56320
	global_load_lds_dwordx4 v[222:223], off
	s_add_i32 m0, s30, 0x2000
	s_add_u32 s28, s28, 0x40080
	v_lshl_add_u64 v[222:223], v[224:225], 0, s[58:59]
	s_addc_u32 s29, s29, 0
	s_add_i32 s30, s54, s40
	global_load_lds_dwordx4 v[222:223], off
	v_lshl_add_u64 v[222:223], s[28:29], 0, v[64:65]
	s_mov_b32 m0, s30
	s_nop 0
	global_load_lds_dwordx4 v[222:223], off
	v_lshl_add_u64 v[222:223], s[28:29], 0, v[150:151]
	s_add_i32 m0, s30, 0x2000
	s_nop 0
	global_load_lds_dwordx4 v[222:223], off
	v_lshl_add_u64 v[222:223], v[226:227], 0, s[58:59]
	s_mov_b32 m0, s49
	s_nop 0
	global_load_lds_dwordx4 v[222:223], off
	v_lshl_add_u64 v[222:223], v[228:229], 0, s[58:59]
	s_mov_b32 m0, s50
	s_nop 0
	global_load_lds_dwordx4 v[222:223], off
	s_waitcnt vmcnt(8)
	s_waitcnt lgkmcnt(0)
	s_barrier
	s_setprio 1
	s_waitcnt lgkmcnt(0)
	v_mfma_f32_16x16x32_bf16 v[60:63], v[130:133], v[176:179], v[60:63]
	v_mfma_f32_16x16x32_bf16 v[56:59], v[138:141], v[176:179], v[56:59]
	v_mfma_f32_16x16x32_bf16 v[44:47], v[130:133], v[184:187], v[44:47]
	v_mfma_f32_16x16x32_bf16 v[40:43], v[138:141], v[184:187], v[40:43]
	v_mfma_f32_16x16x32_bf16 v[28:31], v[130:133], v[206:209], v[28:31]
	v_mfma_f32_16x16x32_bf16 v[24:27], v[138:141], v[206:209], v[24:27]
	v_mfma_f32_16x16x32_bf16 v[12:15], v[130:133], v[214:217], v[12:15]
	v_mfma_f32_16x16x32_bf16 v[8:11], v[138:141], v[214:217], v[8:11]
	v_mfma_f32_16x16x32_bf16 v[60:63], v[134:137], v[180:183], v[60:63]
	v_mfma_f32_16x16x32_bf16 v[56:59], v[142:145], v[180:183], v[56:59]
	v_mfma_f32_16x16x32_bf16 v[44:47], v[134:137], v[188:191], v[44:47]
	v_mfma_f32_16x16x32_bf16 v[40:43], v[142:145], v[188:191], v[40:43]
	v_mfma_f32_16x16x32_bf16 v[28:31], v[134:137], v[210:213], v[28:31]
	v_mfma_f32_16x16x32_bf16 v[24:27], v[142:145], v[210:213], v[24:27]
	v_mfma_f32_16x16x32_bf16 v[12:15], v[134:137], v[218:221], v[12:15]
	v_mfma_f32_16x16x32_bf16 v[8:11], v[142:145], v[218:221], v[8:11]
	v_mfma_f32_16x16x32_bf16 v[52:55], v[146:149], v[176:179], v[52:55]
	v_mfma_f32_16x16x32_bf16 v[48:51], v[164:167], v[176:179], v[48:51]
	v_mfma_f32_16x16x32_bf16 v[36:39], v[146:149], v[184:187], v[36:39]
	v_mfma_f32_16x16x32_bf16 v[32:35], v[164:167], v[184:187], v[32:35]
	v_mfma_f32_16x16x32_bf16 v[20:23], v[146:149], v[206:209], v[20:23]
	v_mfma_f32_16x16x32_bf16 v[16:19], v[164:167], v[206:209], v[16:19]
	v_mfma_f32_16x16x32_bf16 v[4:7], v[146:149], v[214:217], v[4:7]
	v_mfma_f32_16x16x32_bf16 v[0:3], v[164:167], v[214:217], v[0:3]
	v_mfma_f32_16x16x32_bf16 v[52:55], v[160:163], v[180:183], v[52:55]
	v_mfma_f32_16x16x32_bf16 v[48:51], v[168:171], v[180:183], v[48:51]
	v_mfma_f32_16x16x32_bf16 v[36:39], v[160:163], v[188:191], v[36:39]
	v_mfma_f32_16x16x32_bf16 v[32:35], v[168:171], v[188:191], v[32:35]
	v_mfma_f32_16x16x32_bf16 v[20:23], v[160:163], v[210:213], v[20:23]
	v_mfma_f32_16x16x32_bf16 v[16:19], v[168:171], v[210:213], v[16:19]
	v_mfma_f32_16x16x32_bf16 v[4:7], v[160:163], v[218:221], v[4:7]
	v_mfma_f32_16x16x32_bf16 v[0:3], v[168:171], v[218:221], v[0:3]
	s_setprio 0
	s_barrier
	s_add_i32 s52, s52, 2
	s_add_u32 s24, s24, 0x100
	s_addc_u32 s25, s25, 0
	s_add_u32 s27, s27, 0x100
	s_addc_u32 s33, s33, 0
	s_cmp_gt_u32 s52, 13
	s_cbranch_scc0 .LBB0_849
	s_and_b64 vcc, exec, s[8:9]
	s_cbranch_vccz .LBB0_852
	s_barrier

; #define PG8_STAGE(bufoff, gbase, voff) do { _Pragma("unroll") for (int _i = 0; _i < 2; ++_i) \
;         __builtin_amdgcn_global_load_lds((const unsigned*)((const char*)(gbase) + (voff)[_i]), (PG8_LAS unsigned*)(lds + (bufoff) + ldsw + _i * 8192), 16, 0, 0); } while (0)
; #define PG8_LDA(dst, b, h) do { _Pragma("unroll") for (int m = 0; m < 4; ++m) _Pragma("unroll") for (int k = 0; k < 2; ++k) dst[m][k] = *(const PG8_LAS bf16x8*)(lds + PG8_SA(b, h) + aoff + m * 2048 + k * 1024); } while (0)
; #define PG8_LDB(dst, b, h) do { _Pragma("unroll") for (int n = 0; n < 2; ++n) _Pragma("unroll") for (int k = 0; k < 2; ++k) dst[n][k] = *(const PG8_LAS bf16x8*)(lds + PG8_SB(b, h) + boff + n * 2048 + k * 1024); } while (0)
; #define PG8_WAIT_V(n) asm volatile("s_waitcnt vmcnt(" #n ")" ::: "memory")
; #define PG8_WAIT_L(n) asm volatile("s_waitcnt lgkmcnt(" #n ")" ::: "memory")
; #define PG8_BAR __builtin_amdgcn_s_barrier()
; #define PG8_SCHED __builtin_amdgcn_sched_barrier(0)
;     ...
;             const bool last = (t == nt - 2);
;             const char* a1 = cA + (size_t)(t + 1) * kstep;
;             const char* a2 = last ? nA : cA + (size_t)(t + 2) * kstep; const char* b2 = last ? nB : cB + (size_t)(t + 2) * kstep;
;             const char* a3 = a2 + kstep; const char* b3 = b2 + kstep;
;             if (last && has_next) S.a_ready(nxt);
;             if constexpr (SP2) {
;             PG8_LDB(B0, 0, 0); PG8_LDB(B1, 0, 1); PG8_SCHED; PG8_LDA(At, 0, 0); PG8_STAGE(PG8_SA(1, 1), a1 + hstepA, voffA);
;             PG8_WAIT_V(8); PG8_WAIT_L(0); PG8_BAR; PG8_MMA(0, 0, At, B0); PG8_MMA(0, 1, At, B1); PG8_BAR; PG8_SCHED;
;             PG8_LDA(At, 0, 1); PG8_STAGE(PG8_SB(0, 0), b2, voffB); PG8_STAGE(PG8_SB(0, 1), b2 + hstepB, voffB); PG8_STAGE(PG8_SA(0, 0), a2, voffA);
;             PG8_WAIT_V(8); PG8_WAIT_L(0); PG8_BAR; PG8_MMA(1, 0, At, B0); PG8_MMA(1, 1, At, B1); PG8_BAR; PG8_SCHED;
.LBB0_917:
	s_add_u32 s30, s28, 0xfffc0080
	s_addc_u32 s31, s29, -1
	s_add_i32 s51, 0, 0x10000
	s_cmp_eq_u32 s50, 12
	s_cselect_b32 s35, s19, s31
	s_cselect_b32 s34, s21, s30
	s_cselect_b32 s31, s15, s33
	s_cselect_b32 s30, s26, s27
	s_add_i32 s54, 0, 0x14000
	v_add_u32_e32 v142, s51, v190
	v_add_u32_e32 v158, s54, v190
	ds_read_b128 v[130:133], v142
	ds_read_b128 v[134:137], v142 offset:1024
	ds_read_b128 v[138:141], v142 offset:2048
	ds_read_b128 v[142:145], v142 offset:3072
	ds_read_b128 v[146:149], v158
	ds_read_b128 v[150:153], v158 offset:1024
	ds_read_b128 v[154:157], v158 offset:2048
	ds_read_b128 v[158:161], v158 offset:3072
	v_lshl_add_u64 v[222:223], s[28:29], 0, v[176:177]
	s_add_i32 m0, s39, 0xc000
	ds_read_b128 v[162:165], v191
	ds_read_b128 v[166:169], v191 offset:1024
	ds_read_b128 v[180:183], v191 offset:2048
	ds_read_b128 v[184:187], v191 offset:3072
	ds_read_b128 v[206:209], v191 offset:4096
	ds_read_b128 v[210:213], v191 offset:5120
	ds_read_b128 v[214:217], v191 offset:6144
	ds_read_b128 v[218:221], v191 offset:7168
	global_load_lds_dwordx4 v[222:223], off
	v_lshl_add_u64 v[222:223], s[28:29], 0, v[178:179]
	s_add_i32 m0, s39, 0xe000
	s_nop 0
	global_load_lds_dwordx4 v[222:223], off
	s_waitcnt vmcnt(8)
	s_waitcnt lgkmcnt(0)
	s_barrier
	s_setprio 1
	s_waitcnt lgkmcnt(0)
	v_mfma_f32_16x16x32_f16 v[126:129], v[130:133], v[162:165], v[126:129]
	v_mfma_f32_16x16x32_f16 v[122:125], v[138:141], v[162:165], v[122:125]
	v_mfma_f32_16x16x32_f16 v[110:113], v[130:133], v[180:183], v[110:113]
	v_mfma_f32_16x16x32_f16 v[106:109], v[138:141], v[180:183], v[106:109]
	v_mfma_f32_16x16x32_f16 v[94:97], v[130:133], v[206:209], v[94:97]
	v_mfma_f32_16x16x32_f16 v[90:93], v[138:141], v[206:209], v[90:93]
	v_mfma_f32_16x16x32_f16 v[78:81], v[130:133], v[214:217], v[78:81]
	v_mfma_f32_16x16x32_f16 v[74:77], v[138:141], v[214:217], v[74:77]
	v_mfma_f32_16x16x32_f16 v[126:129], v[134:137], v[166:169], v[126:129]
	v_mfma_f32_16x16x32_f16 v[122:125], v[142:145], v[166:169], v[122:125]
	v_mfma_f32_16x16x32_f16 v[110:113], v[134:137], v[184:187], v[110:113]
	v_mfma_f32_16x16x32_f16 v[106:109], v[142:145], v[184:187], v[106:109]
	v_mfma_f32_16x16x32_f16 v[94:97], v[134:137], v[210:213], v[94:97]
	v_mfma_f32_16x16x32_f16 v[90:93], v[142:145], v[210:213], v[90:93]
	v_mfma_f32_16x16x32_f16 v[78:81], v[134:137], v[218:221], v[78:81]
	v_mfma_f32_16x16x32_f16 v[74:77], v[142:145], v[218:221], v[74:77]
	v_mfma_f32_16x16x32_f16 v[118:121], v[146:149], v[162:165], v[118:121]
	v_mfma_f32_16x16x32_f16 v[114:117], v[154:157], v[162:165], v[114:117]
	v_mfma_f32_16x16x32_f16 v[102:105], v[146:149], v[180:183], v[102:105]
	v_mfma_f32_16x16x32_f16 v[98:101], v[154:157], v[180:183], v[98:101]
	v_mfma_f32_16x16x32_f16 v[86:89], v[146:149], v[206:209], v[86:89]
	v_mfma_f32_16x16x32_f16 v[82:85], v[154:157], v[206:209], v[82:85]
	v_mfma_f32_16x16x32_f16 v[70:73], v[146:149], v[214:217], v[70:73]
	v_mfma_f32_16x16x32_f16 v[66:69], v[154:157], v[214:217], v[66:69]
	v_mfma_f32_16x16x32_f16 v[118:121], v[150:153], v[166:169], v[118:121]
	v_mfma_f32_16x16x32_f16 v[114:117], v[158:161], v[166:169], v[114:117]
	v_mfma_f32_16x16x32_f16 v[102:105], v[150:153], v[184:187], v[102:105]
	v_mfma_f32_16x16x32_f16 v[98:101], v[158:161], v[184:187], v[98:101]
	v_mfma_f32_16x16x32_f16 v[86:89], v[150:153], v[210:213], v[86:89]
	v_mfma_f32_16x16x32_f16 v[82:85], v[158:161], v[210:213], v[82:85]
	v_mfma_f32_16x16x32_f16 v[70:73], v[150:153], v[218:221], v[70:73]
	v_mfma_f32_16x16x32_f16 v[66:69], v[158:161], v[218:221], v[66:69]
	s_setprio 0
	s_barrier
	s_add_i32 s51, s51, s38
	v_lshl_add_u64 v[222:223], s[30:31], 0, v[64:65]
	s_mov_b32 m0, s51
	ds_read_b128 v[162:165], v191 offset:16384
	ds_read_b128 v[166:169], v191 offset:17408
	ds_read_b128 v[180:183], v191 offset:18432
	ds_read_b128 v[184:187], v191 offset:19456
	ds_read_b128 v[206:209], v191 offset:20480
	ds_read_b128 v[210:213], v191 offset:21504
	ds_read_b128 v[214:217], v191 offset:22528
	ds_read_b128 v[218:221], v191 offset:23552
	global_load_lds_dwordx4 v[222:223], off
	s_add_i32 m0, s51, 0x2000
	s_add_u32 s52, s30, 0x40000
	v_lshl_add_u64 v[224:225], s[30:31], 0, v[170:171]
	s_addc_u32 s53, s31, 0
	s_add_i32 s51, s54, s38
	global_load_lds_dwordx4 v[224:225], off
	v_lshl_add_u64 v[226:227], s[52:53], 0, v[64:65]
	s_mov_b32 m0, s51
	v_lshl_add_u64 v[228:229], s[34:35], 0, v[172:173]
	global_load_lds_dwordx4 v[226:227], off
	v_lshl_add_u64 v[226:227], s[52:53], 0, v[170:171]
	s_add_i32 m0, s51, 0x2000
	s_nop 0
	global_load_lds_dwordx4 v[226:227], off
	v_lshl_add_u64 v[226:227], s[34:35], 0, v[174:175]
	s_mov_b32 m0, s39
	s_nop 0
	global_load_lds_dwordx4 v[226:227], off
	s_mov_b32 m0, s40
	s_nop 0
	global_load_lds_dwordx4 v[228:229], off
	s_waitcnt vmcnt(8)
	s_waitcnt lgkmcnt(0)
	s_barrier
; #define PG8_STAGE(bufoff, gbase, voff) do { _Pragma("unroll") for (int _i = 0; _i < 2; ++_i) \
;         __builtin_amdgcn_global_load_lds((const unsigned*)((const char*)(gbase) + (voff)[_i]), (PG8_LAS unsigned*)(lds + (bufoff) + ldsw + _i * 8192), 16, 0, 0); } while (0)
; #define PG8_LDA(dst, b, h) do { _Pragma("unroll") for (int m = 0; m < 4; ++m) _Pragma("unroll") for (int k = 0; k < 2; ++k) dst[m][k] = *(const PG8_LAS bf16x8*)(lds + PG8_SA(b, h) + aoff + m * 2048 + k * 1024); } while (0)
; #define PG8_LDB(dst, b, h) do { _Pragma("unroll") for (int n = 0; n < 2; ++n) _Pragma("unroll") for (int k = 0; k < 2; ++k) dst[n][k] = *(const PG8_LAS bf16x8*)(lds + PG8_SB(b, h) + boff + n * 2048 + k * 1024); } while (0)
; #define PG8_WAIT_V(n) asm volatile("s_waitcnt vmcnt(" #n ")" ::: "memory")
; #define PG8_WAIT_L(n) asm volatile("s_waitcnt lgkmcnt(" #n ")" ::: "memory")
; #define PG8_BAR __builtin_amdgcn_s_barrier()
; #define PG8_SCHED __builtin_amdgcn_sched_barrier(0)
;     ...
;             PG8_WAIT_V(8); PG8_WAIT_L(0); PG8_BAR; PG8_MMA(1, 0, At, B0); PG8_MMA(1, 1, At, B1); PG8_BAR; PG8_SCHED;
;             PG8_LDB(B0, 1, 0); PG8_LDB(B1, 1, 1); PG8_SCHED; PG8_LDA(At, 1, 0); PG8_STAGE(PG8_SA(0, 1), a2 + hstepA, voffA);
;             PG8_WAIT_V(8); PG8_WAIT_L(0); PG8_BAR; PG8_MMA(0, 0, At, B0); PG8_MMA(0, 1, At, B1); PG8_BAR; PG8_SCHED;
	s_setprio 1
	s_waitcnt lgkmcnt(0)
	v_mfma_f32_16x16x32_f16 v[60:63], v[130:133], v[162:165], v[60:63]
	v_mfma_f32_16x16x32_f16 v[56:59], v[138:141], v[162:165], v[56:59]
	v_mfma_f32_16x16x32_f16 v[44:47], v[130:133], v[180:183], v[44:47]
	v_mfma_f32_16x16x32_f16 v[40:43], v[138:141], v[180:183], v[40:43]
	v_mfma_f32_16x16x32_f16 v[28:31], v[130:133], v[206:209], v[28:31]
	v_mfma_f32_16x16x32_f16 v[24:27], v[138:141], v[206:209], v[24:27]
	v_mfma_f32_16x16x32_f16 v[12:15], v[130:133], v[214:217], v[12:15]
	v_mfma_f32_16x16x32_f16 v[8:11], v[138:141], v[214:217], v[8:11]
	v_mfma_f32_16x16x32_f16 v[60:63], v[134:137], v[166:169], v[60:63]
	v_mfma_f32_16x16x32_f16 v[56:59], v[142:145], v[166:169], v[56:59]
	v_mfma_f32_16x16x32_f16 v[44:47], v[134:137], v[184:187], v[44:47]
	v_mfma_f32_16x16x32_f16 v[40:43], v[142:145], v[184:187], v[40:43]
	v_mfma_f32_16x16x32_f16 v[28:31], v[134:137], v[210:213], v[28:31]
	v_mfma_f32_16x16x32_f16 v[24:27], v[142:145], v[210:213], v[24:27]
	v_mfma_f32_16x16x32_f16 v[12:15], v[134:137], v[218:221], v[12:15]
	v_mfma_f32_16x16x32_f16 v[8:11], v[142:145], v[218:221], v[8:11]
	v_mfma_f32_16x16x32_f16 v[52:55], v[146:149], v[162:165], v[52:55]
	v_mfma_f32_16x16x32_f16 v[48:51], v[154:157], v[162:165], v[48:51]
	v_mfma_f32_16x16x32_f16 v[36:39], v[146:149], v[180:183], v[36:39]
	v_mfma_f32_16x16x32_f16 v[32:35], v[154:157], v[180:183], v[32:35]
	v_mfma_f32_16x16x32_f16 v[20:23], v[146:149], v[206:209], v[20:23]
	v_mfma_f32_16x16x32_f16 v[16:19], v[154:157], v[206:209], v[16:19]
	v_mfma_f32_16x16x32_f16 v[4:7], v[146:149], v[214:217], v[4:7]
	v_mfma_f32_16x16x32_f16 v[0:3], v[154:157], v[214:217], v[0:3]
	v_mfma_f32_16x16x32_f16 v[52:55], v[150:153], v[166:169], v[52:55]
	v_mfma_f32_16x16x32_f16 v[48:51], v[158:161], v[166:169], v[48:51]
	v_mfma_f32_16x16x32_f16 v[36:39], v[150:153], v[184:187], v[36:39]
	v_mfma_f32_16x16x32_f16 v[32:35], v[158:161], v[184:187], v[32:35]
	v_mfma_f32_16x16x32_f16 v[20:23], v[150:153], v[210:213], v[20:23]
	v_mfma_f32_16x16x32_f16 v[16:19], v[158:161], v[210:213], v[16:19]
	v_mfma_f32_16x16x32_f16 v[4:7], v[150:153], v[218:221], v[4:7]
	v_mfma_f32_16x16x32_f16 v[0:3], v[158:161], v[218:221], v[0:3]
	s_setprio 0
	s_barrier
	s_add_i32 s51, 0, 0x18000
	s_add_i32 s52, 0, 0x1c000
	v_add_u32_e32 v142, s51, v190
	v_add_u32_e32 v158, s52, v190
	ds_read_b128 v[130:133], v142
	ds_read_b128 v[134:137], v142 offset:1024
	ds_read_b128 v[138:141], v142 offset:2048
	ds_read_b128 v[142:145], v142 offset:3072
	ds_read_b128 v[146:149], v158
	ds_read_b128 v[150:153], v158 offset:1024
	ds_read_b128 v[154:157], v158 offset:2048
	ds_read_b128 v[158:161], v158 offset:3072
	s_add_u32 s34, s34, 0x40000
	s_addc_u32 s35, s35, 0
	s_mov_b32 m0, s41
	v_lshl_add_u64 v[230:231], s[34:35], 0, v[174:175]
	ds_read_b128 v[162:165], v191 offset:32768
	ds_read_b128 v[166:169], v191 offset:33792
	ds_read_b128 v[180:183], v191 offset:34816
	ds_read_b128 v[184:187], v191 offset:35840
	ds_read_b128 v[206:209], v191 offset:36864
	ds_read_b128 v[210:213], v191 offset:37888
	ds_read_b128 v[214:217], v191 offset:38912
	ds_read_b128 v[218:221], v191 offset:39936
	global_load_lds_dwordx4 v[230:231], off
	v_lshl_add_u64 v[230:231], s[34:35], 0, v[172:173]
	s_mov_b32 m0, s44
	s_nop 0
	global_load_lds_dwordx4 v[230:231], off
	s_waitcnt vmcnt(8)
	s_waitcnt lgkmcnt(0)
	s_barrier
	s_setprio 1
	s_waitcnt lgkmcnt(0)
	v_mfma_f32_16x16x32_f16 v[126:129], v[130:133], v[162:165], v[126:129]
	v_mfma_f32_16x16x32_f16 v[122:125], v[138:141], v[162:165], v[122:125]
	v_mfma_f32_16x16x32_f16 v[110:113], v[130:133], v[180:183], v[110:113]
	v_mfma_f32_16x16x32_f16 v[106:109], v[138:141], v[180:183], v[106:109]
	v_mfma_f32_16x16x32_f16 v[94:97], v[130:133], v[206:209], v[94:97]
	v_mfma_f32_16x16x32_f16 v[90:93], v[138:141], v[206:209], v[90:93]
	v_mfma_f32_16x16x32_f16 v[78:81], v[130:133], v[214:217], v[78:81]
	v_mfma_f32_16x16x32_f16 v[74:77], v[138:141], v[214:217], v[74:77]
	v_mfma_f32_16x16x32_f16 v[126:129], v[134:137], v[166:169], v[126:129]
	v_mfma_f32_16x16x32_f16 v[122:125], v[142:145], v[166:169], v[122:125]
	v_mfma_f32_16x16x32_f16 v[110:113], v[134:137], v[184:187], v[110:113]
	v_mfma_f32_16x16x32_f16 v[106:109], v[142:145], v[184:187], v[106:109]
	v_mfma_f32_16x16x32_f16 v[94:97], v[134:137], v[210:213], v[94:97]
	v_mfma_f32_16x16x32_f16 v[90:93], v[142:145], v[210:213], v[90:93]
	v_mfma_f32_16x16x32_f16 v[78:81], v[134:137], v[218:221], v[78:81]
	v_mfma_f32_16x16x32_f16 v[74:77], v[142:145], v[218:221], v[74:77]
	v_mfma_f32_16x16x32_f16 v[118:121], v[146:149], v[162:165], v[118:121]
	v_mfma_f32_16x16x32_f16 v[114:117], v[154:157], v[162:165], v[114:117]
	v_mfma_f32_16x16x32_f16 v[102:105], v[146:149], v[180:183], v[102:105]
	v_mfma_f32_16x16x32_f16 v[98:101], v[154:157], v[180:183], v[98:101]
	v_mfma_f32_16x16x32_f16 v[86:89], v[146:149], v[206:209], v[86:89]
	v_mfma_f32_16x16x32_f16 v[82:85], v[154:157], v[206:209], v[82:85]
	v_mfma_f32_16x16x32_f16 v[70:73], v[146:149], v[214:217], v[70:73]
	v_mfma_f32_16x16x32_f16 v[66:69], v[154:157], v[214:217], v[66:69]
	v_mfma_f32_16x16x32_f16 v[118:121], v[150:153], v[166:169], v[118:121]
	v_mfma_f32_16x16x32_f16 v[114:117], v[158:161], v[166:169], v[114:117]
	v_mfma_f32_16x16x32_f16 v[102:105], v[150:153], v[184:187], v[102:105]
	v_mfma_f32_16x16x32_f16 v[98:101], v[158:161], v[184:187], v[98:101]
	v_mfma_f32_16x16x32_f16 v[86:89], v[150:153], v[210:213], v[86:89]
	v_mfma_f32_16x16x32_f16 v[82:85], v[158:161], v[210:213], v[82:85]
	v_mfma_f32_16x16x32_f16 v[70:73], v[150:153], v[218:221], v[70:73]
	v_mfma_f32_16x16x32_f16 v[66:69], v[158:161], v[218:221], v[66:69]
	s_setprio 0
	s_barrier
; #define PG8_STAGE(bufoff, gbase, voff) do { _Pragma("unroll") for (int _i = 0; _i < 2; ++_i) \
;         __builtin_amdgcn_global_load_lds((const unsigned*)((const char*)(gbase) + (voff)[_i]), (PG8_LAS unsigned*)(lds + (bufoff) + ldsw + _i * 8192), 16, 0, 0); } while (0)
; #define PG8_LDA(dst, b, h) do { _Pragma("unroll") for (int m = 0; m < 4; ++m) _Pragma("unroll") for (int k = 0; k < 2; ++k) dst[m][k] = *(const PG8_LAS bf16x8*)(lds + PG8_SA(b, h) + aoff + m * 2048 + k * 1024); } while (0)
; #define PG8_WAIT_V(n) asm volatile("s_waitcnt vmcnt(" #n ")" ::: "memory")
; #define PG8_WAIT_L(n) asm volatile("s_waitcnt lgkmcnt(" #n ")" ::: "memory")
; #define PG8_BAR __builtin_amdgcn_s_barrier()
; #define PG8_SCHED __builtin_amdgcn_sched_barrier(0)
;     ...
;             PG8_LDA(At, 1, 1); PG8_STAGE(PG8_SB(1, 0), b3, voffB); PG8_STAGE(PG8_SB(1, 1), b3 + hstepB, voffB); PG8_STAGE(PG8_SA(1, 0), a3, voffA);
;             PG8_WAIT_V(8); PG8_WAIT_L(0); PG8_BAR; PG8_MMA(1, 0, At, B0); PG8_MMA(1, 1, At, B1); PG8_BAR; PG8_SCHED;
;     ...
;         if constexpr (ALIGN_EPI) { if (wr == 0) PG8_BAR; }
	s_add_i32 s34, s51, s38
	v_lshl_add_u64 v[222:223], v[222:223], 0, s[56:57]
	s_mov_b32 m0, s34
	ds_read_b128 v[162:165], v191 offset:49152
	ds_read_b128 v[166:169], v191 offset:50176
	ds_read_b128 v[180:183], v191 offset:51200
	ds_read_b128 v[184:187], v191 offset:52224
	ds_read_b128 v[206:209], v191 offset:53248
	ds_read_b128 v[210:213], v191 offset:54272
	ds_read_b128 v[214:217], v191 offset:55296
	ds_read_b128 v[218:221], v191 offset:56320
	global_load_lds_dwordx4 v[222:223], off
	s_add_i32 m0, s34, 0x2000
	s_add_u32 s30, s30, 0x40080
	v_lshl_add_u64 v[222:223], v[224:225], 0, s[56:57]
	s_addc_u32 s31, s31, 0
	s_add_i32 s34, s52, s38
	global_load_lds_dwordx4 v[222:223], off
	v_lshl_add_u64 v[222:223], s[30:31], 0, v[64:65]
	s_mov_b32 m0, s34
	s_nop 0
	global_load_lds_dwordx4 v[222:223], off
	v_lshl_add_u64 v[222:223], s[30:31], 0, v[170:171]
	s_add_i32 m0, s34, 0x2000
	s_nop 0
	global_load_lds_dwordx4 v[222:223], off
	v_lshl_add_u64 v[222:223], v[226:227], 0, s[56:57]
	s_mov_b32 m0, s47
	s_nop 0
	global_load_lds_dwordx4 v[222:223], off
	v_lshl_add_u64 v[222:223], v[228:229], 0, s[56:57]
	s_mov_b32 m0, s48
	s_nop 0
	global_load_lds_dwordx4 v[222:223], off
	s_waitcnt vmcnt(8)
	s_waitcnt lgkmcnt(0)
	s_barrier
	s_setprio 1
	s_waitcnt lgkmcnt(0)
	v_mfma_f32_16x16x32_f16 v[60:63], v[130:133], v[162:165], v[60:63]
	v_mfma_f32_16x16x32_f16 v[56:59], v[138:141], v[162:165], v[56:59]
	v_mfma_f32_16x16x32_f16 v[44:47], v[130:133], v[180:183], v[44:47]
	v_mfma_f32_16x16x32_f16 v[40:43], v[138:141], v[180:183], v[40:43]
	v_mfma_f32_16x16x32_f16 v[28:31], v[130:133], v[206:209], v[28:31]
	v_mfma_f32_16x16x32_f16 v[24:27], v[138:141], v[206:209], v[24:27]
	v_mfma_f32_16x16x32_f16 v[12:15], v[130:133], v[214:217], v[12:15]
	v_mfma_f32_16x16x32_f16 v[8:11], v[138:141], v[214:217], v[8:11]
	v_mfma_f32_16x16x32_f16 v[60:63], v[134:137], v[166:169], v[60:63]
	v_mfma_f32_16x16x32_f16 v[56:59], v[142:145], v[166:169], v[56:59]
	v_mfma_f32_16x16x32_f16 v[44:47], v[134:137], v[184:187], v[44:47]
	v_mfma_f32_16x16x32_f16 v[40:43], v[142:145], v[184:187], v[40:43]
	v_mfma_f32_16x16x32_f16 v[28:31], v[134:137], v[210:213], v[28:31]
	v_mfma_f32_16x16x32_f16 v[24:27], v[142:145], v[210:213], v[24:27]
	v_mfma_f32_16x16x32_f16 v[12:15], v[134:137], v[218:221], v[12:15]
	v_mfma_f32_16x16x32_f16 v[8:11], v[142:145], v[218:221], v[8:11]
	v_mfma_f32_16x16x32_f16 v[52:55], v[146:149], v[162:165], v[52:55]
	v_mfma_f32_16x16x32_f16 v[48:51], v[154:157], v[162:165], v[48:51]
	v_mfma_f32_16x16x32_f16 v[36:39], v[146:149], v[180:183], v[36:39]
	v_mfma_f32_16x16x32_f16 v[32:35], v[154:157], v[180:183], v[32:35]
	v_mfma_f32_16x16x32_f16 v[20:23], v[146:149], v[206:209], v[20:23]
	v_mfma_f32_16x16x32_f16 v[16:19], v[154:157], v[206:209], v[16:19]
	v_mfma_f32_16x16x32_f16 v[4:7], v[146:149], v[214:217], v[4:7]
	v_mfma_f32_16x16x32_f16 v[0:3], v[154:157], v[214:217], v[0:3]
	v_mfma_f32_16x16x32_f16 v[52:55], v[150:153], v[166:169], v[52:55]
	v_mfma_f32_16x16x32_f16 v[48:51], v[158:161], v[166:169], v[48:51]
	v_mfma_f32_16x16x32_f16 v[36:39], v[150:153], v[184:187], v[36:39]
	v_mfma_f32_16x16x32_f16 v[32:35], v[158:161], v[184:187], v[32:35]
	v_mfma_f32_16x16x32_f16 v[20:23], v[150:153], v[210:213], v[20:23]
	v_mfma_f32_16x16x32_f16 v[16:19], v[158:161], v[210:213], v[16:19]
	v_mfma_f32_16x16x32_f16 v[4:7], v[150:153], v[218:221], v[4:7]
	v_mfma_f32_16x16x32_f16 v[0:3], v[158:161], v[218:221], v[0:3]
	s_setprio 0
	s_barrier
	s_add_i32 s50, s50, 2
	s_add_u32 s28, s28, 0x100
	s_addc_u32 s29, s29, 0
	s_add_u32 s27, s27, 0x100
	s_addc_u32 s33, s33, 0
	s_cmp_gt_u32 s50, 13
	s_cbranch_scc0 .LBB0_917
	s_and_b64 vcc, exec, s[12:13]
	s_cbranch_vccz .LBB0_920
	s_barrier
